# stack18 plus nt hint on the first-row (prologue) x/D loads of every residual+norm pass
# speedup vs baseline: 1.0007x; 1.0007x over previous
.LBB0_306:
	s_add_u32 s4, s94, 0x1b500000
	s_addc_u32 s5, s95, 0
	v_writelane_b32 v254, s4, 60
	s_cmp_lt_i32 s42, 4
	s_nop 0
	v_writelane_b32 v254, s5, 61
	s_cselect_b64 s[4:5], -1, 0
	s_cmp_gt_i32 s43, 3
	s_cselect_b64 s[6:7], -1, 0
	s_and_b64 s[4:5], s[4:5], s[6:7]
	s_andn2_b64 vcc, exec, s[4:5]
	s_cbranch_vccnz .LBB0_378
	s_load_dwordx16 s[4:19], s[0:1], 0x0
	s_waitcnt lgkmcnt(0)
	s_mov_b64 s[4:5], s[8:9]
	s_mov_b64 s[6:7], s[10:11]
	s_mov_b64 s[8:9], s[12:13]
	s_mov_b64 s[10:11], s[14:15]
	s_mov_b64 s[12:13], s[16:17]
	s_mov_b64 s[14:15], s[18:19]
	s_add_u32 s4, s14, 0x2000
	s_addc_u32 s5, s15, 0
	s_add_u32 s6, s14, 0x4000
	s_addc_u32 s7, s15, 0
	s_ashr_i32 s9, s90, 5
	s_abs_i32 s8, s9
	v_cvt_f32_u32_e32 v169, s8
	s_sub_i32 s12, 0, s8
	s_abs_i32 s10, s62
	s_xor_b32 s11, s62, s9
	v_rcp_iflag_f32_e32 v169, v169
	s_ashr_i32 s11, s11, 31
	v_mul_f32_e32 v169, 0x4f7ffffe, v169
	v_cvt_u32_f32_e32 v169, v169
	s_nop 0
	v_readfirstlane_b32 s13, v169
	s_mul_i32 s12, s12, s13
	s_mul_hi_u32 s12, s13, s12
	s_add_i32 s13, s13, s12
	s_mul_hi_u32 s12, s10, s13
	s_mul_i32 s13, s12, s8
	s_sub_i32 s10, s10, s13
	s_add_i32 s14, s12, 1
	s_sub_i32 s13, s10, s8
	s_cmp_ge_u32 s10, s8
	s_cselect_b32 s12, s14, s12
	s_cselect_b32 s10, s13, s10
	s_add_i32 s13, s12, 1
	s_cmp_ge_u32 s10, s8
	s_cselect_b32 s8, s13, s12
	s_xor_b32 s8, s8, s11
	s_sub_i32 s8, s8, s11
	s_mul_i32 s9, s8, s9
	s_sub_i32 s9, s62, s9
	s_cmp_lg_u32 s9, 0
	s_ashr_i32 s9, s8, 31
	s_lshl_b64 s[10:11], s[8:9], 13
	v_readlane_b32 s12, v254, 58
	v_readlane_b32 s13, v254, 59
	s_add_u32 s10, s12, s10
	s_addc_u32 s11, s13, s11
	v_mov_b32_e32 v181, 0
	v_lshlrev_b32_e32 v180, 4, v0
	v_lshl_add_u64 v[170:171], s[10:11], 0, v[180:181]
	v_add_co_u32_e32 v172, vcc, 0x40000, v170
	global_load_dwordx4 v[186:189], v180, s[10:11]
	s_nop 0
	v_addc_co_u32_e32 v173, vcc, 0, v171, vcc
	v_add_co_u32_e32 v174, vcc, 0x80000, v170
	s_addk_i32 s8, 0x2000
	s_nop 0
	v_addc_co_u32_e32 v175, vcc, 0, v171, vcc
	v_add_co_u32_e32 v170, vcc, 0xc0000, v170
	global_load_dwordx4 v[190:193], v[172:173], off
	global_load_dwordx4 v[194:197], v[174:175], off
	v_addc_co_u32_e32 v171, vcc, 0, v171, vcc
	global_load_dwordx4 v[198:201], v[170:171], off
	s_ashr_i32 s9, s8, 31
	s_lshl_b64 s[10:11], s[8:9], 12
	v_readlane_b32 s12, v254, 54
	v_readlane_b32 s13, v254, 55
	s_add_u32 s10, s12, s10
	s_addc_u32 s11, s13, s11
	v_lshlrev_b32_e32 v178, 3, v0
	global_load_dwordx4 v[174:177], v180, s[4:5]
	global_load_dwordx4 v[170:173], v180, s[6:7]
	global_load_dwordx2 v[182:183], v178, s[10:11]
	s_lshl_b32 s9, s62, 3
	s_add_i32 s8, s9, s96
	s_and_b32 s9, s9, 0xf8
	s_lshl_b32 s10, s62, 5
	s_add_i32 s9, s9, s96
	s_and_b32 s10, s10, 0xfffffc00
	s_add_i32 s9, s9, s10
	s_add_i32 s14, s9, 0x400
	s_cmpk_eq_i32 s90, 0x100
	s_cselect_b64 s[12:13], -1, 0
	s_and_b64 s[10:11], s[12:13], exec
	s_cselect_b32 s10, s9, s8
	s_cselect_b32 s9, s14, 0x2000
	s_cmp_ge_i32 s10, s9
	s_cbranch_scc1 .LBB0_312
	s_lshl_b32 s11, s90, 3
	v_lshlrev_b32_e32 v1, 5, v166
	s_and_b64 s[12:13], s[12:13], exec
	v_or_b32_e32 v46, 0x800, v1
	v_or_b32_e32 v54, 0x1000, v1
	v_or_b32_e32 v62, 0x1800, v1
	s_cselect_b32 s12, 0x100, s11
	s_ashr_i32 s11, s10, 31
	global_load_dwordx4 v[2:5], v1, s[4:5] offset:16
	global_load_dwordx4 v[6:9], v1, s[4:5]
	global_load_dwordx4 v[10:13], v46, s[4:5] offset:16
	global_load_dwordx4 v[14:17], v46, s[4:5]
	global_load_dwordx4 v[18:21], v54, s[4:5] offset:16
	global_load_dwordx4 v[22:25], v54, s[4:5]
	global_load_dwordx4 v[26:29], v62, s[4:5] offset:16
	global_load_dwordx4 v[30:33], v62, s[4:5]
	global_load_dwordx4 v[34:37], v1, s[6:7] offset:16
	global_load_dwordx4 v[38:41], v1, s[6:7]
	global_load_dwordx4 v[42:45], v46, s[6:7] offset:16
	s_nop 0
	global_load_dwordx4 v[46:49], v46, s[6:7]
	s_nop 0
	global_load_dwordx4 v[50:53], v54, s[6:7] offset:16
	s_nop 0
	global_load_dwordx4 v[54:57], v54, s[6:7]
	s_lshl_b64 s[14:15], s[10:11], 12
	v_readlane_b32 s16, v254, 54
	v_readlane_b32 s17, v254, 55
	s_add_u32 s16, s16, s14
	s_addc_u32 s17, s17, s15
	s_add_u32 s18, s80, s14
	v_lshlrev_b32_e32 v130, 4, v166
	s_addc_u32 s19, s81, s15
	global_load_dwordx4 v[110:113], v130, s[16:17] nt
	global_load_dwordx4 v[106:109], v130, s[16:17] offset:1024 nt
	global_load_dwordx4 v[102:105], v130, s[16:17] offset:2048 nt
	global_load_dwordx4 v[126:129], v130, s[18:19] nt
	global_load_dwordx4 v[122:125], v130, s[18:19] offset:1024 nt
	global_load_dwordx4 v[98:101], v130, s[16:17] offset:3072 nt
	global_load_dwordx4 v[118:121], v130, s[18:19] offset:2048 nt
	global_load_dwordx4 v[114:117], v130, s[18:19] offset:3072 nt
	global_load_dwordx4 v[58:61], v62, s[6:7] offset:16
	s_nop 0
	global_load_dwordx4 v[62:65], v62, s[6:7]
	s_add_u32 s14, s94, s14
	s_addc_u32 s15, s95, s15
	s_add_i32 s18, s10, s12
	s_ashr_i32 s13, s12, 31
	s_ashr_i32 s19, s18, 31
	s_lshl_b64 s[16:17], s[12:13], 12
	s_lshl_b64 s[18:19], s[18:19], 12
	s_add_u32 s18, s94, s18
	v_mov_b32_e32 v131, 0
	s_mov_b32 s11, 0x2f1e0000
	s_mov_b32 s22, 0x2f1e1000
	v_mov_b32_e32 v1, 0x358637bd
	s_mov_b32 s23, 0x1b500000
	v_mov_b32_e32 v132, 0x3a000000
	s_addc_u32 s19, s95, s19
	s_waitcnt vmcnt(9)
	v_mov_b64_e32 v[66:67], v[110:111]
	s_waitcnt vmcnt(8)
	v_mov_b64_e32 v[70:71], v[106:107]
	s_waitcnt vmcnt(7)
	v_mov_b64_e32 v[78:79], v[102:103]
	s_waitcnt vmcnt(6)
	v_mov_b64_e32 v[74:75], v[126:127]
	s_waitcnt vmcnt(5)
	v_mov_b64_e32 v[82:83], v[122:123]
	s_waitcnt vmcnt(4)
	v_mov_b64_e32 v[94:95], v[98:99]
	s_waitcnt vmcnt(3)
	v_mov_b64_e32 v[86:87], v[118:119]
	s_waitcnt vmcnt(2)
	v_mov_b64_e32 v[90:91], v[114:115]
	v_mov_b64_e32 v[68:69], v[112:113]
	v_mov_b64_e32 v[72:73], v[108:109]
	v_mov_b64_e32 v[80:81], v[104:105]
	v_mov_b64_e32 v[76:77], v[128:129]
	v_mov_b64_e32 v[84:85], v[124:125]
	v_mov_b64_e32 v[88:89], v[120:121]
	v_mov_b64_e32 v[92:93], v[116:117]
	v_mov_b64_e32 v[96:97], v[100:101]
	s_branch .LBB0_310

.LBB0_635:
	s_cmp_lt_i32 s42, 8
	s_cselect_b64 s[4:5], -1, 0
	s_cmp_gt_i32 s43, 7
	s_cselect_b64 s[6:7], -1, 0
	s_and_b64 s[4:5], s[4:5], s[6:7]
	s_andn2_b64 vcc, exec, s[4:5]
	s_cbranch_vccnz .LBB0_715
	s_load_dwordx16 s[4:19], s[0:1], 0x0
	s_waitcnt lgkmcnt(0)
	s_mov_b64 s[8:9], s[12:13]
	s_mov_b64 s[10:11], s[14:15]
	s_mov_b64 s[12:13], s[16:17]
	s_mov_b64 s[14:15], s[18:19]
	s_add_u32 s8, s14, 0x6000
	s_addc_u32 s9, s15, 0
	s_add_u32 s10, s14, 0x8000
	s_addc_u32 s11, s15, 0
	s_ashr_i32 s5, s90, 5
	s_abs_i32 s4, s5
	v_cvt_f32_u32_e32 v169, s4
	s_sub_i32 s12, 0, s4
	s_abs_i32 s6, s62
	s_xor_b32 s7, s62, s5
	v_rcp_iflag_f32_e32 v169, v169
	s_ashr_i32 s7, s7, 31
	v_mul_f32_e32 v169, 0x4f7ffffe, v169
	v_cvt_u32_f32_e32 v169, v169
	s_nop 0
	v_readfirstlane_b32 s13, v169
	s_mul_i32 s12, s12, s13
	s_mul_hi_u32 s12, s13, s12
	s_add_i32 s13, s13, s12
	s_mul_hi_u32 s12, s6, s13
	s_mul_i32 s13, s12, s4
	s_sub_i32 s6, s6, s13
	s_add_i32 s14, s12, 1
	s_sub_i32 s13, s6, s4
	s_cmp_ge_u32 s6, s4
	s_cselect_b32 s12, s14, s12
	s_cselect_b32 s6, s13, s6
	s_add_i32 s13, s12, 1
	s_cmp_ge_u32 s6, s4
	s_cselect_b32 s4, s13, s12
	s_xor_b32 s4, s4, s7
	s_sub_i32 s4, s4, s7
	s_mul_i32 s5, s4, s5
	s_sub_i32 s5, s62, s5
	s_cmp_lg_u32 s5, 0
	s_ashr_i32 s5, s4, 31
	s_lshl_b64 s[6:7], s[4:5], 13
	v_readlane_b32 s12, v254, 58
	v_readlane_b32 s13, v254, 59
	s_add_u32 s6, s12, s6
	s_addc_u32 s7, s13, s7
	v_mov_b32_e32 v179, 0
	v_lshlrev_b32_e32 v178, 4, v0
	v_lshl_add_u64 v[170:171], s[6:7], 0, v[178:179]
	v_add_co_u32_e32 v172, vcc, 0x40000, v170
	global_load_dwordx4 v[184:187], v178, s[6:7]
	s_nop 0
	v_addc_co_u32_e32 v173, vcc, 0, v171, vcc
	v_add_co_u32_e32 v174, vcc, 0x80000, v170
	s_add_i32 s6, s4, 0x2000
	s_nop 0
	v_addc_co_u32_e32 v175, vcc, 0, v171, vcc
	v_add_co_u32_e32 v170, vcc, 0xc0000, v170
	global_load_dwordx4 v[188:191], v[172:173], off
	global_load_dwordx4 v[192:195], v[174:175], off
	v_addc_co_u32_e32 v171, vcc, 0, v171, vcc
	global_load_dwordx4 v[196:199], v[170:171], off
	s_ashr_i32 s7, s6, 31
	s_lshl_b64 s[4:5], s[6:7], 12
	v_readlane_b32 s12, v254, 54
	v_readlane_b32 s13, v254, 55
	s_add_u32 s4, s12, s4
	s_addc_u32 s5, s13, s5
	v_lshlrev_b32_e32 v182, 3, v0
	global_load_dwordx4 v[174:177], v178, s[8:9]
	global_load_dwordx4 v[170:173], v178, s[10:11]
	global_load_dwordx2 v[180:181], v182, s[4:5]
	s_lshl_b32 s4, s62, 3
	s_add_i32 s12, s4, s96
	s_and_b32 s4, s4, 0xf8
	s_lshl_b32 s5, s62, 5
	s_add_i32 s4, s4, s96
	s_and_b32 s5, s5, 0xfffffc00
	s_add_i32 s13, s4, s5
	s_add_i32 s15, s13, 0x400
	s_cmpk_eq_i32 s90, 0x100
	s_cselect_b64 s[4:5], -1, 0
	s_and_b64 s[6:7], s[4:5], exec
	s_cselect_b32 s14, s13, s12
	s_cselect_b32 s13, s15, 0x2000
	s_cmp_ge_i32 s14, s13
	s_cbranch_scc1 .LBB0_643
	s_lshl_b32 s6, s90, 3
	v_lshlrev_b32_e32 v1, 5, v166
	s_and_b64 s[4:5], s[4:5], exec
	v_or_b32_e32 v46, 0x800, v1
	v_or_b32_e32 v54, 0x1000, v1
	v_or_b32_e32 v62, 0x1800, v1
	s_cselect_b32 s16, 0x100, s6
	s_ashr_i32 s15, s14, 31
	global_load_dwordx4 v[2:5], v1, s[8:9] offset:16
	global_load_dwordx4 v[6:9], v1, s[8:9]
	global_load_dwordx4 v[10:13], v46, s[8:9] offset:16
	global_load_dwordx4 v[14:17], v46, s[8:9]
	global_load_dwordx4 v[18:21], v54, s[8:9] offset:16
	global_load_dwordx4 v[22:25], v54, s[8:9]
	global_load_dwordx4 v[26:29], v62, s[8:9] offset:16
	global_load_dwordx4 v[30:33], v62, s[8:9]
	global_load_dwordx4 v[34:37], v1, s[10:11] offset:16
	global_load_dwordx4 v[38:41], v1, s[10:11]
	global_load_dwordx4 v[42:45], v46, s[10:11] offset:16
	s_nop 0
	global_load_dwordx4 v[46:49], v46, s[10:11]
	s_nop 0
	global_load_dwordx4 v[50:53], v54, s[10:11] offset:16
	s_nop 0
	global_load_dwordx4 v[54:57], v54, s[10:11]
	s_lshl_b64 s[6:7], s[14:15], 11
	s_lshl_b64 s[18:19], s[14:15], 12
	v_readlane_b32 s4, v254, 54
	v_readlane_b32 s5, v254, 55
	s_add_u32 s4, s4, s18
	s_addc_u32 s5, s5, s19
	s_add_u32 s20, s80, s18
	v_lshlrev_b32_e32 v66, 4, v166
	s_addc_u32 s21, s81, s19
	global_load_dwordx4 v[110:113], v66, s[4:5] nt
	global_load_dwordx4 v[106:109], v66, s[4:5] offset:1024 nt
	global_load_dwordx4 v[102:105], v66, s[4:5] offset:2048 nt
	global_load_dwordx4 v[126:129], v66, s[20:21] nt
	global_load_dwordx4 v[122:125], v66, s[20:21] offset:1024 nt
	global_load_dwordx4 v[98:101], v66, s[4:5] offset:3072 nt
	global_load_dwordx4 v[118:121], v66, s[20:21] offset:2048 nt
	global_load_dwordx4 v[114:117], v66, s[20:21] offset:3072 nt
	global_load_dwordx4 v[58:61], v62, s[10:11] offset:16
	s_nop 0
	global_load_dwordx4 v[62:65], v62, s[10:11]
	v_lshl_or_b32 v130, v166, 3, s6
	v_mov_b32_e32 v131, s7
	s_lshl_b64 s[6:7], s[14:15], 2
	s_add_u32 s15, s6, 0x2ee80000
	s_addc_u32 s37, s7, 0
	s_add_i32 s6, s14, s16
	s_ashr_i32 s7, s6, 31
	s_lshl_b64 s[6:7], s[6:7], 12
	v_or_b32_e32 v132, s18, v66
	s_ashr_i32 s17, s16, 31
	v_or_b32_e32 v134, s6, v66
	v_cmp_eq_u32_e64 s[4:5], 0, v166
	s_mov_b32 s28, 0x2f1e0000
	s_mov_b32 s29, 0x2f1e1000
	v_mov_b32_e32 v1, 0
	v_mov_b32_e32 v136, 0x358637bd
	s_mov_b32 s30, 0x42fe0000
	s_mov_b32 s31, 0xc0c0400
	s_mov_b32 s34, 0xc040100
	s_mov_b32 s35, 0x4020100
	s_mov_b32 s36, 0x2de00000
	v_mov_b32_e32 v137, 0x3a000000
	v_mov_b32_e32 v138, 0x3c010204
	v_mov_b32_e32 v139, 0x42fe0000
	v_mov_b32_e32 v133, s19
	s_lshl_b64 s[18:19], s[16:17], 2
	s_lshl_b64 s[20:21], s[16:17], 11
	s_lshl_b64 s[22:23], s[16:17], 12
	v_mov_b32_e32 v135, s7
	s_waitcnt vmcnt(9)
	v_mov_b64_e32 v[66:67], v[110:111]
	s_waitcnt vmcnt(8)
	v_mov_b64_e32 v[70:71], v[106:107]
	s_waitcnt vmcnt(7)
	v_mov_b64_e32 v[78:79], v[102:103]
	s_waitcnt vmcnt(6)
	v_mov_b64_e32 v[74:75], v[126:127]
	s_waitcnt vmcnt(5)
	v_mov_b64_e32 v[82:83], v[122:123]
	s_waitcnt vmcnt(4)
	v_mov_b64_e32 v[94:95], v[98:99]
	s_waitcnt vmcnt(3)
	v_mov_b64_e32 v[86:87], v[118:119]
	s_waitcnt vmcnt(2)
	v_mov_b64_e32 v[90:91], v[114:115]
	v_mov_b64_e32 v[68:69], v[112:113]
	v_mov_b64_e32 v[72:73], v[108:109]
	v_mov_b64_e32 v[80:81], v[104:105]
	v_mov_b64_e32 v[76:77], v[128:129]
	v_mov_b64_e32 v[84:85], v[124:125]
	v_mov_b64_e32 v[88:89], v[120:121]
	v_mov_b64_e32 v[92:93], v[116:117]
	v_mov_b64_e32 v[96:97], v[100:101]
	s_branch .LBB0_639

.LBB0_906:
	s_cmp_lt_i32 s42, 11
	s_cselect_b64 s[4:5], -1, 0
	s_cmp_gt_i32 s43, 10
	s_cselect_b64 s[6:7], -1, 0
	s_and_b64 s[4:5], s[4:5], s[6:7]
	s_andn2_b64 vcc, exec, s[4:5]
	s_cbranch_vccnz .LBB0_986
	s_load_dwordx16 s[4:19], s[0:1], 0x0
	s_waitcnt lgkmcnt(0)
	s_mov_b64 s[8:9], s[12:13]
	s_mov_b64 s[10:11], s[14:15]
	s_mov_b64 s[12:13], s[16:17]
	s_mov_b64 s[14:15], s[18:19]
	s_add_u32 s8, s14, 0xa000
	s_addc_u32 s9, s15, 0
	s_add_u32 s10, s14, 0xc000
	s_addc_u32 s11, s15, 0
	s_ashr_i32 s5, s90, 5
	s_abs_i32 s4, s5
	v_cvt_f32_u32_e32 v169, s4
	s_sub_i32 s12, 0, s4
	s_abs_i32 s6, s62
	s_xor_b32 s7, s62, s5
	v_rcp_iflag_f32_e32 v169, v169
	s_ashr_i32 s7, s7, 31
	v_mul_f32_e32 v169, 0x4f7ffffe, v169
	v_cvt_u32_f32_e32 v169, v169
	s_nop 0
	v_readfirstlane_b32 s13, v169
	s_mul_i32 s12, s12, s13
	s_mul_hi_u32 s12, s13, s12
	s_add_i32 s13, s13, s12
	s_mul_hi_u32 s12, s6, s13
	s_mul_i32 s13, s12, s4
	s_sub_i32 s6, s6, s13
	s_add_i32 s14, s12, 1
	s_sub_i32 s13, s6, s4
	s_cmp_ge_u32 s6, s4
	s_cselect_b32 s12, s14, s12
	s_cselect_b32 s6, s13, s6
	s_add_i32 s13, s12, 1
	s_cmp_ge_u32 s6, s4
	s_cselect_b32 s4, s13, s12
	s_xor_b32 s4, s4, s7
	s_sub_i32 s4, s4, s7
	s_mul_i32 s5, s4, s5
	s_sub_i32 s5, s62, s5
	s_cmp_lg_u32 s5, 0
	s_ashr_i32 s5, s4, 31
	s_lshl_b64 s[6:7], s[4:5], 13
	v_readlane_b32 s12, v254, 58
	v_readlane_b32 s13, v254, 59
	s_add_u32 s6, s12, s6
	s_addc_u32 s7, s13, s7
	v_mov_b32_e32 v179, 0
	v_lshlrev_b32_e32 v178, 4, v0
	v_lshl_add_u64 v[170:171], s[6:7], 0, v[178:179]
	v_add_co_u32_e32 v172, vcc, 0x40000, v170
	global_load_dwordx4 v[184:187], v178, s[6:7]
	s_nop 0
	v_addc_co_u32_e32 v173, vcc, 0, v171, vcc
	v_add_co_u32_e32 v174, vcc, 0x80000, v170
	s_add_i32 s6, s4, 0x2000
	s_nop 0
	v_addc_co_u32_e32 v175, vcc, 0, v171, vcc
	v_add_co_u32_e32 v170, vcc, 0xc0000, v170
	global_load_dwordx4 v[188:191], v[172:173], off
	global_load_dwordx4 v[192:195], v[174:175], off
	v_addc_co_u32_e32 v171, vcc, 0, v171, vcc
	global_load_dwordx4 v[196:199], v[170:171], off
	s_ashr_i32 s7, s6, 31
	s_lshl_b64 s[4:5], s[6:7], 12
	v_readlane_b32 s12, v254, 54
	v_readlane_b32 s13, v254, 55
	s_add_u32 s4, s12, s4
	s_addc_u32 s5, s13, s5
	v_lshlrev_b32_e32 v182, 3, v0
	global_load_dwordx4 v[174:177], v178, s[8:9]
	global_load_dwordx4 v[170:173], v178, s[10:11]
	global_load_dwordx2 v[180:181], v182, s[4:5]
	s_lshl_b32 s4, s62, 3
	s_add_i32 s12, s4, s96
	s_and_b32 s4, s4, 0xf8
	s_lshl_b32 s5, s62, 5
	s_add_i32 s4, s4, s96
	s_and_b32 s5, s5, 0xfffffc00
	s_add_i32 s13, s4, s5
	s_add_i32 s15, s13, 0x400
	s_cmpk_eq_i32 s90, 0x100
	s_cselect_b64 s[4:5], -1, 0
	s_and_b64 s[6:7], s[4:5], exec
	s_cselect_b32 s14, s13, s12
	s_cselect_b32 s13, s15, 0x2000
	s_cmp_ge_i32 s14, s13
	s_cbranch_scc1 .LBB0_914
	s_lshl_b32 s6, s90, 3
	v_lshlrev_b32_e32 v1, 5, v166
	s_and_b64 s[4:5], s[4:5], exec
	v_or_b32_e32 v46, 0x800, v1
	v_or_b32_e32 v54, 0x1000, v1
	v_or_b32_e32 v62, 0x1800, v1
	s_cselect_b32 s16, 0x100, s6
	s_ashr_i32 s15, s14, 31
	global_load_dwordx4 v[2:5], v1, s[8:9] offset:16
	global_load_dwordx4 v[6:9], v1, s[8:9]
	global_load_dwordx4 v[10:13], v46, s[8:9] offset:16
	global_load_dwordx4 v[14:17], v46, s[8:9]
	global_load_dwordx4 v[18:21], v54, s[8:9] offset:16
	global_load_dwordx4 v[22:25], v54, s[8:9]
	global_load_dwordx4 v[26:29], v62, s[8:9] offset:16
	global_load_dwordx4 v[30:33], v62, s[8:9]
	global_load_dwordx4 v[34:37], v1, s[10:11] offset:16
	global_load_dwordx4 v[38:41], v1, s[10:11]
	global_load_dwordx4 v[42:45], v46, s[10:11] offset:16
	s_nop 0
	global_load_dwordx4 v[46:49], v46, s[10:11]
	s_nop 0
	global_load_dwordx4 v[50:53], v54, s[10:11] offset:16
	s_nop 0
	global_load_dwordx4 v[54:57], v54, s[10:11]
	s_lshl_b64 s[6:7], s[14:15], 11
	s_lshl_b64 s[18:19], s[14:15], 12
	v_readlane_b32 s4, v254, 54
	v_readlane_b32 s5, v254, 55
	s_add_u32 s4, s4, s18
	s_addc_u32 s5, s5, s19
	s_add_u32 s20, s80, s18
	v_lshlrev_b32_e32 v66, 4, v166
	s_addc_u32 s21, s81, s19
	global_load_dwordx4 v[110:113], v66, s[4:5] nt
	global_load_dwordx4 v[106:109], v66, s[4:5] offset:1024 nt
	global_load_dwordx4 v[102:105], v66, s[4:5] offset:2048 nt
	global_load_dwordx4 v[126:129], v66, s[20:21] nt
	global_load_dwordx4 v[122:125], v66, s[20:21] offset:1024 nt
	global_load_dwordx4 v[98:101], v66, s[4:5] offset:3072 nt
	global_load_dwordx4 v[118:121], v66, s[20:21] offset:2048 nt
	global_load_dwordx4 v[114:117], v66, s[20:21] offset:3072 nt
	global_load_dwordx4 v[58:61], v62, s[10:11] offset:16
	s_nop 0
	global_load_dwordx4 v[62:65], v62, s[10:11]
	v_lshl_or_b32 v130, v166, 3, s6
	v_mov_b32_e32 v131, s7
	s_lshl_b64 s[6:7], s[14:15], 2
	s_add_u32 s15, s6, 0x2ee80000
	s_addc_u32 s37, s7, 0
	s_add_i32 s6, s14, s16
	s_ashr_i32 s7, s6, 31
	s_lshl_b64 s[6:7], s[6:7], 12
	v_or_b32_e32 v132, s18, v66
	s_ashr_i32 s17, s16, 31
	v_or_b32_e32 v134, s6, v66
	v_cmp_eq_u32_e64 s[4:5], 0, v166
	s_mov_b32 s28, 0x2f1e0000
	s_mov_b32 s29, 0x2f1e1000
	v_mov_b32_e32 v1, 0
	v_mov_b32_e32 v136, 0x358637bd
	s_mov_b32 s30, 0x42fe0000
	s_mov_b32 s31, 0xc0c0400
	s_mov_b32 s34, 0xc040100
	s_mov_b32 s35, 0x4020100
	s_mov_b32 s36, 0x2de00000
	v_mov_b32_e32 v137, 0x3a000000
	v_mov_b32_e32 v138, 0x3c010204
	v_mov_b32_e32 v139, 0x42fe0000
	v_mov_b32_e32 v133, s19
	s_lshl_b64 s[18:19], s[16:17], 2
	s_lshl_b64 s[20:21], s[16:17], 11
	s_lshl_b64 s[22:23], s[16:17], 12
	v_mov_b32_e32 v135, s7
	s_waitcnt vmcnt(9)
	v_mov_b64_e32 v[66:67], v[110:111]
	s_waitcnt vmcnt(8)
	v_mov_b64_e32 v[70:71], v[106:107]
	s_waitcnt vmcnt(7)
	v_mov_b64_e32 v[78:79], v[102:103]
	s_waitcnt vmcnt(6)
	v_mov_b64_e32 v[74:75], v[126:127]
	s_waitcnt vmcnt(5)
	v_mov_b64_e32 v[82:83], v[122:123]
	s_waitcnt vmcnt(4)
	v_mov_b64_e32 v[94:95], v[98:99]
	s_waitcnt vmcnt(3)
	v_mov_b64_e32 v[86:87], v[118:119]
	s_waitcnt vmcnt(2)
	v_mov_b64_e32 v[90:91], v[114:115]
	v_mov_b64_e32 v[68:69], v[112:113]
	v_mov_b64_e32 v[72:73], v[108:109]
	v_mov_b64_e32 v[80:81], v[104:105]
	v_mov_b64_e32 v[76:77], v[128:129]
	v_mov_b64_e32 v[84:85], v[124:125]
	v_mov_b64_e32 v[88:89], v[120:121]
	v_mov_b64_e32 v[92:93], v[116:117]
	v_mov_b64_e32 v[96:97], v[100:101]
	s_branch .LBB0_910

.LBB0_1177:
	s_cmp_lt_i32 s42, 14
	s_cselect_b64 s[4:5], -1, 0
	s_cmp_gt_i32 s43, 13
	s_cselect_b64 s[6:7], -1, 0
	s_and_b64 s[4:5], s[4:5], s[6:7]
	s_andn2_b64 vcc, exec, s[4:5]
	s_cbranch_vccnz .LBB0_1249
	s_load_dwordx16 s[4:19], s[0:1], 0x0
	s_waitcnt lgkmcnt(0)
	s_mov_b64 s[8:9], s[12:13]
	s_mov_b64 s[10:11], s[14:15]
	s_mov_b64 s[12:13], s[16:17]
	s_mov_b64 s[14:15], s[18:19]
	s_add_u32 s4, s14, 0xe000
	s_addc_u32 s5, s15, 0
	s_add_u32 s6, s14, 0x10000
	s_addc_u32 s7, s15, 0
	s_ashr_i32 s9, s90, 5
	s_abs_i32 s8, s9
	v_cvt_f32_u32_e32 v169, s8
	s_sub_i32 s12, 0, s8
	s_abs_i32 s10, s62
	s_xor_b32 s11, s62, s9
	v_rcp_iflag_f32_e32 v169, v169
	s_ashr_i32 s11, s11, 31
	v_mul_f32_e32 v169, 0x4f7ffffe, v169
	v_cvt_u32_f32_e32 v169, v169
	s_nop 0
	v_readfirstlane_b32 s13, v169
	s_mul_i32 s12, s12, s13
	s_mul_hi_u32 s12, s13, s12
	s_add_i32 s13, s13, s12
	s_mul_hi_u32 s12, s10, s13
	s_mul_i32 s13, s12, s8
	s_sub_i32 s10, s10, s13
	s_add_i32 s14, s12, 1
	s_sub_i32 s13, s10, s8
	s_cmp_ge_u32 s10, s8
	s_cselect_b32 s12, s14, s12
	s_cselect_b32 s10, s13, s10
	s_add_i32 s13, s12, 1
	s_cmp_ge_u32 s10, s8
	s_cselect_b32 s8, s13, s12
	s_xor_b32 s8, s8, s11
	s_sub_i32 s8, s8, s11
	s_mul_i32 s9, s8, s9
	s_sub_i32 s9, s62, s9
	s_cmp_lg_u32 s9, 0
	s_ashr_i32 s9, s8, 31
	s_lshl_b64 s[10:11], s[8:9], 13
	v_readlane_b32 s12, v254, 58
	v_readlane_b32 s13, v254, 59
	s_add_u32 s10, s12, s10
	s_addc_u32 s11, s13, s11
	v_mov_b32_e32 v181, 0
	v_lshlrev_b32_e32 v180, 4, v0
	v_lshl_add_u64 v[170:171], s[10:11], 0, v[180:181]
	v_add_co_u32_e32 v172, vcc, 0x40000, v170
	global_load_dwordx4 v[186:189], v180, s[10:11]
	s_nop 0
	v_addc_co_u32_e32 v173, vcc, 0, v171, vcc
	v_add_co_u32_e32 v174, vcc, 0x80000, v170
	s_addk_i32 s8, 0x2000
	s_nop 0
	v_addc_co_u32_e32 v175, vcc, 0, v171, vcc
	v_add_co_u32_e32 v170, vcc, 0xc0000, v170
	global_load_dwordx4 v[190:193], v[172:173], off
	global_load_dwordx4 v[194:197], v[174:175], off
	v_addc_co_u32_e32 v171, vcc, 0, v171, vcc
	global_load_dwordx4 v[198:201], v[170:171], off
	s_ashr_i32 s9, s8, 31
	s_lshl_b64 s[10:11], s[8:9], 12
	v_readlane_b32 s12, v254, 54
	v_readlane_b32 s13, v254, 55
	s_add_u32 s10, s12, s10
	s_addc_u32 s11, s13, s11
	v_lshlrev_b32_e32 v178, 3, v0
	global_load_dwordx4 v[174:177], v180, s[4:5]
	global_load_dwordx4 v[170:173], v180, s[6:7]
	global_load_dwordx2 v[182:183], v178, s[10:11]
	s_lshl_b32 s9, s62, 3
	s_add_i32 s8, s9, s96
	s_and_b32 s9, s9, 0xf8
	s_lshl_b32 s10, s62, 5
	s_add_i32 s9, s9, s96
	s_and_b32 s10, s10, 0xfffffc00
	s_add_i32 s9, s9, s10
	s_add_i32 s14, s9, 0x400
	s_cmpk_eq_i32 s90, 0x100
	s_cselect_b64 s[12:13], -1, 0
	s_and_b64 s[10:11], s[12:13], exec
	s_cselect_b32 s10, s9, s8
	s_cselect_b32 s9, s14, 0x2000
	s_cmp_ge_i32 s10, s9
	s_cbranch_scc1 .LBB0_1183
	s_lshl_b32 s11, s90, 3
	v_lshlrev_b32_e32 v1, 5, v166
	s_and_b64 s[12:13], s[12:13], exec
	v_or_b32_e32 v46, 0x800, v1
	v_or_b32_e32 v54, 0x1000, v1
	v_or_b32_e32 v62, 0x1800, v1
	s_cselect_b32 s12, 0x100, s11
	s_ashr_i32 s11, s10, 31
	global_load_dwordx4 v[2:5], v1, s[4:5] offset:16
	global_load_dwordx4 v[6:9], v1, s[4:5]
	global_load_dwordx4 v[10:13], v46, s[4:5] offset:16
	global_load_dwordx4 v[14:17], v46, s[4:5]
	global_load_dwordx4 v[18:21], v54, s[4:5] offset:16
	global_load_dwordx4 v[22:25], v54, s[4:5]
	global_load_dwordx4 v[26:29], v62, s[4:5] offset:16
	global_load_dwordx4 v[30:33], v62, s[4:5]
	global_load_dwordx4 v[34:37], v1, s[6:7] offset:16
	global_load_dwordx4 v[38:41], v1, s[6:7]
	global_load_dwordx4 v[42:45], v46, s[6:7] offset:16
	s_nop 0
	global_load_dwordx4 v[46:49], v46, s[6:7]
	s_nop 0
	global_load_dwordx4 v[50:53], v54, s[6:7] offset:16
	s_nop 0
	global_load_dwordx4 v[54:57], v54, s[6:7]
	s_lshl_b64 s[14:15], s[10:11], 12
	v_readlane_b32 s16, v254, 54
	v_readlane_b32 s17, v254, 55
	s_add_u32 s16, s16, s14
	s_addc_u32 s17, s17, s15
	s_add_u32 s18, s80, s14
	v_lshlrev_b32_e32 v130, 4, v166
	s_addc_u32 s19, s81, s15
	global_load_dwordx4 v[110:113], v130, s[16:17] nt
	global_load_dwordx4 v[106:109], v130, s[16:17] offset:1024 nt
	global_load_dwordx4 v[102:105], v130, s[16:17] offset:2048 nt
	global_load_dwordx4 v[126:129], v130, s[18:19] nt
	global_load_dwordx4 v[122:125], v130, s[18:19] offset:1024 nt
	global_load_dwordx4 v[98:101], v130, s[16:17] offset:3072 nt
	global_load_dwordx4 v[118:121], v130, s[18:19] offset:2048 nt
	global_load_dwordx4 v[114:117], v130, s[18:19] offset:3072 nt
	global_load_dwordx4 v[58:61], v62, s[6:7] offset:16
	s_nop 0
	global_load_dwordx4 v[62:65], v62, s[6:7]
	s_add_u32 s14, s94, s14
	s_addc_u32 s15, s95, s15
	s_add_i32 s18, s10, s12
	s_ashr_i32 s13, s12, 31
	s_ashr_i32 s19, s18, 31
	s_lshl_b64 s[16:17], s[12:13], 12
	s_lshl_b64 s[18:19], s[18:19], 12
	s_add_u32 s18, s94, s18
	v_mov_b32_e32 v131, 0
	s_mov_b32 s11, 0x2f1e0000
	s_mov_b32 s22, 0x2f1e1000
	v_mov_b32_e32 v1, 0x358637bd
	s_mov_b32 s23, 0x1b500000
	v_mov_b32_e32 v132, 0x3a000000
	s_addc_u32 s19, s95, s19
	s_waitcnt vmcnt(9)
	v_mov_b64_e32 v[66:67], v[110:111]
	s_waitcnt vmcnt(8)
	v_mov_b64_e32 v[70:71], v[106:107]
	s_waitcnt vmcnt(7)
	v_mov_b64_e32 v[78:79], v[102:103]
	s_waitcnt vmcnt(6)
	v_mov_b64_e32 v[74:75], v[126:127]
	s_waitcnt vmcnt(5)
	v_mov_b64_e32 v[82:83], v[122:123]
	s_waitcnt vmcnt(4)
	v_mov_b64_e32 v[94:95], v[98:99]
	s_waitcnt vmcnt(3)
	v_mov_b64_e32 v[86:87], v[118:119]
	s_waitcnt vmcnt(2)
	v_mov_b64_e32 v[90:91], v[114:115]
	v_mov_b64_e32 v[68:69], v[112:113]
	v_mov_b64_e32 v[72:73], v[108:109]
	v_mov_b64_e32 v[80:81], v[104:105]
	v_mov_b64_e32 v[76:77], v[128:129]
	v_mov_b64_e32 v[84:85], v[124:125]
	v_mov_b64_e32 v[88:89], v[120:121]
	v_mov_b64_e32 v[92:93], v[116:117]
	v_mov_b64_e32 v[96:97], v[100:101]
	s_branch .LBB0_1181

.LBB0_1493:
	s_cmp_lt_i32 s42, 18
	s_cselect_b64 s[4:5], -1, 0
	s_cmp_gt_i32 s43, 17
	s_cselect_b64 s[6:7], -1, 0
	s_and_b64 s[4:5], s[4:5], s[6:7]
	s_andn2_b64 vcc, exec, s[4:5]
	s_cbranch_vccnz .LBB0_1573
	s_load_dwordx16 s[64:79], s[0:1], 0x0
	s_waitcnt lgkmcnt(0)
	s_mov_b64 s[12:13], s[76:77]
	s_mov_b64 s[14:15], s[78:79]
	s_add_u32 s8, s14, 0x12000
	s_addc_u32 s9, s15, 0
	s_add_u32 s10, s14, 0x14000
	s_addc_u32 s11, s15, 0
	s_ashr_i32 s5, s90, 5
	s_abs_i32 s4, s5
	v_cvt_f32_u32_e32 v169, s4
	s_sub_i32 s12, 0, s4
	s_abs_i32 s6, s62
	s_xor_b32 s7, s62, s5
	v_rcp_iflag_f32_e32 v169, v169
	s_ashr_i32 s7, s7, 31
	v_mul_f32_e32 v169, 0x4f7ffffe, v169
	v_cvt_u32_f32_e32 v169, v169
	s_nop 0
	v_readfirstlane_b32 s13, v169
	s_mul_i32 s12, s12, s13
	s_mul_hi_u32 s12, s13, s12
	s_add_i32 s13, s13, s12
	s_mul_hi_u32 s12, s6, s13
	s_mul_i32 s13, s12, s4
	s_sub_i32 s6, s6, s13
	s_add_i32 s14, s12, 1
	s_sub_i32 s13, s6, s4
	s_cmp_ge_u32 s6, s4
	s_cselect_b32 s12, s14, s12
	s_cselect_b32 s6, s13, s6
	s_add_i32 s13, s12, 1
	s_cmp_ge_u32 s6, s4
	s_cselect_b32 s4, s13, s12
	s_xor_b32 s4, s4, s7
	s_sub_i32 s4, s4, s7
	s_mul_i32 s5, s4, s5
	s_sub_i32 s5, s62, s5
	s_cmp_lg_u32 s5, 0
	s_ashr_i32 s5, s4, 31
	s_lshl_b64 s[6:7], s[4:5], 13
	v_readlane_b32 s12, v254, 58
	v_readlane_b32 s13, v254, 59
	s_add_u32 s6, s12, s6
	s_addc_u32 s7, s13, s7
	v_mov_b32_e32 v179, 0
	v_lshlrev_b32_e32 v178, 4, v0
	v_lshl_add_u64 v[170:171], s[6:7], 0, v[178:179]
	v_add_co_u32_e32 v172, vcc, 0x40000, v170
	global_load_dwordx4 v[184:187], v178, s[6:7]
	s_nop 0
	v_addc_co_u32_e32 v173, vcc, 0, v171, vcc
	v_add_co_u32_e32 v174, vcc, 0x80000, v170
	s_add_i32 s6, s4, 0x2000
	s_nop 0
	v_addc_co_u32_e32 v175, vcc, 0, v171, vcc
	v_add_co_u32_e32 v170, vcc, 0xc0000, v170
	global_load_dwordx4 v[188:191], v[172:173], off
	global_load_dwordx4 v[192:195], v[174:175], off
	v_addc_co_u32_e32 v171, vcc, 0, v171, vcc
	global_load_dwordx4 v[196:199], v[170:171], off
	s_ashr_i32 s7, s6, 31
	s_lshl_b64 s[4:5], s[6:7], 12
	v_readlane_b32 s12, v254, 54
	v_readlane_b32 s13, v254, 55
	s_add_u32 s4, s12, s4
	s_addc_u32 s5, s13, s5
	v_lshlrev_b32_e32 v182, 3, v0
	global_load_dwordx4 v[174:177], v178, s[8:9]
	global_load_dwordx4 v[170:173], v178, s[10:11]
	global_load_dwordx2 v[180:181], v182, s[4:5]
	s_lshl_b32 s4, s62, 3
	s_add_i32 s12, s4, s96
	s_and_b32 s4, s4, 0xf8
	s_lshl_b32 s5, s62, 5
	s_add_i32 s4, s4, s96
	s_and_b32 s5, s5, 0xfffffc00
	s_add_i32 s13, s4, s5
	s_add_i32 s15, s13, 0x400
	s_cmpk_eq_i32 s90, 0x100
	s_cselect_b64 s[4:5], -1, 0
	s_and_b64 s[6:7], s[4:5], exec
	s_cselect_b32 s14, s13, s12
	s_cselect_b32 s13, s15, 0x2000
	s_cmp_ge_i32 s14, s13
	s_cbranch_scc1 .LBB0_1501
	s_lshl_b32 s6, s90, 3
	v_lshlrev_b32_e32 v1, 5, v166
	s_and_b64 s[4:5], s[4:5], exec
	v_or_b32_e32 v46, 0x800, v1
	v_or_b32_e32 v54, 0x1000, v1
	v_or_b32_e32 v62, 0x1800, v1
	s_cselect_b32 s16, 0x100, s6
	s_ashr_i32 s15, s14, 31
	global_load_dwordx4 v[2:5], v1, s[8:9] offset:16
	global_load_dwordx4 v[6:9], v1, s[8:9]
	global_load_dwordx4 v[10:13], v46, s[8:9] offset:16
	global_load_dwordx4 v[14:17], v46, s[8:9]
	global_load_dwordx4 v[18:21], v54, s[8:9] offset:16
	global_load_dwordx4 v[22:25], v54, s[8:9]
	global_load_dwordx4 v[26:29], v62, s[8:9] offset:16
	global_load_dwordx4 v[30:33], v62, s[8:9]
	global_load_dwordx4 v[34:37], v1, s[10:11] offset:16
	global_load_dwordx4 v[38:41], v1, s[10:11]
	global_load_dwordx4 v[42:45], v46, s[10:11] offset:16
	s_nop 0
	global_load_dwordx4 v[46:49], v46, s[10:11]
	s_nop 0
	global_load_dwordx4 v[50:53], v54, s[10:11] offset:16
	s_nop 0
	global_load_dwordx4 v[54:57], v54, s[10:11]
	s_lshl_b64 s[6:7], s[14:15], 11
	s_lshl_b64 s[20:21], s[14:15], 12
	v_readlane_b32 s4, v254, 54
	v_readlane_b32 s5, v254, 55
	s_add_u32 s4, s4, s20
	s_addc_u32 s5, s5, s21
	s_add_u32 s22, s80, s20
	v_lshlrev_b32_e32 v66, 4, v166
	s_addc_u32 s23, s81, s21
	global_load_dwordx4 v[110:113], v66, s[4:5] nt
	global_load_dwordx4 v[106:109], v66, s[4:5] offset:1024 nt
	global_load_dwordx4 v[102:105], v66, s[4:5] offset:2048 nt
	global_load_dwordx4 v[126:129], v66, s[22:23] nt
	global_load_dwordx4 v[122:125], v66, s[22:23] offset:1024 nt
	global_load_dwordx4 v[98:101], v66, s[4:5] offset:3072 nt
	global_load_dwordx4 v[118:121], v66, s[22:23] offset:2048 nt
	global_load_dwordx4 v[114:117], v66, s[22:23] offset:3072 nt
	global_load_dwordx4 v[58:61], v62, s[10:11] offset:16
	s_nop 0
	global_load_dwordx4 v[62:65], v62, s[10:11]
	v_lshl_or_b32 v130, v166, 3, s6
	v_mov_b32_e32 v131, s7
	s_lshl_b64 s[6:7], s[14:15], 2
	s_add_u32 s15, s6, 0x2ee80000
	s_addc_u32 s39, s7, 0
	s_add_i32 s6, s14, s16
	s_ashr_i32 s7, s6, 31
	s_lshl_b64 s[6:7], s[6:7], 12
	v_or_b32_e32 v132, s20, v66
	s_ashr_i32 s17, s16, 31
	v_or_b32_e32 v134, s6, v66
	v_cmp_eq_u32_e64 s[4:5], 0, v166
	s_mov_b32 s30, 0x2f1e0000
	s_mov_b32 s31, 0x2f1e1000
	v_mov_b32_e32 v1, 0
	v_mov_b32_e32 v136, 0x358637bd
	s_mov_b32 s34, 0x42fe0000
	s_mov_b32 s35, 0xc0c0400
	s_mov_b32 s36, 0xc040100
	s_mov_b32 s37, 0x4020100
	s_mov_b32 s38, 0x2de00000
	v_mov_b32_e32 v137, 0x3a000000
	v_mov_b32_e32 v138, 0x3c010204
	v_mov_b32_e32 v139, 0x42fe0000
	v_mov_b32_e32 v133, s21
	s_lshl_b64 s[20:21], s[16:17], 2
	s_lshl_b64 s[22:23], s[16:17], 11
	s_lshl_b64 s[24:25], s[16:17], 12
	v_mov_b32_e32 v135, s7
	s_waitcnt vmcnt(9)
	v_mov_b64_e32 v[66:67], v[110:111]
	s_waitcnt vmcnt(8)
	v_mov_b64_e32 v[70:71], v[106:107]
	s_waitcnt vmcnt(7)
	v_mov_b64_e32 v[78:79], v[102:103]
	s_waitcnt vmcnt(6)
	v_mov_b64_e32 v[74:75], v[126:127]
	s_waitcnt vmcnt(5)
	v_mov_b64_e32 v[82:83], v[122:123]
	s_waitcnt vmcnt(4)
	v_mov_b64_e32 v[94:95], v[98:99]
	s_waitcnt vmcnt(3)
	v_mov_b64_e32 v[86:87], v[118:119]
	s_waitcnt vmcnt(2)
	v_mov_b64_e32 v[90:91], v[114:115]
	v_mov_b64_e32 v[68:69], v[112:113]
	v_mov_b64_e32 v[72:73], v[108:109]
	v_mov_b64_e32 v[80:81], v[104:105]
	v_mov_b64_e32 v[76:77], v[128:129]
	v_mov_b64_e32 v[84:85], v[124:125]
	v_mov_b64_e32 v[88:89], v[120:121]
	v_mov_b64_e32 v[92:93], v[116:117]
	v_mov_b64_e32 v[96:97], v[100:101]
	s_branch .LBB0_1497

.LBB0_1764:
	s_cmp_lt_i32 s42, 21
	s_cselect_b64 s[4:5], -1, 0
	s_cmp_gt_i32 s43, 20
	s_cselect_b64 s[6:7], -1, 0
	s_and_b64 s[4:5], s[4:5], s[6:7]
	s_andn2_b64 vcc, exec, s[4:5]
	s_cbranch_vccnz .LBB0_1844
	s_load_dwordx16 s[64:79], s[0:1], 0x0
	s_waitcnt lgkmcnt(0)
	s_mov_b64 s[12:13], s[76:77]
	s_mov_b64 s[14:15], s[78:79]
	s_add_u32 s8, s14, 0x16000
	s_addc_u32 s9, s15, 0
	s_add_u32 s10, s14, 0x18000
	s_addc_u32 s11, s15, 0
	s_ashr_i32 s5, s90, 5
	s_abs_i32 s4, s5
	v_cvt_f32_u32_e32 v169, s4
	s_sub_i32 s12, 0, s4
	s_abs_i32 s6, s62
	s_xor_b32 s7, s62, s5
	v_rcp_iflag_f32_e32 v169, v169
	s_ashr_i32 s7, s7, 31
	v_mul_f32_e32 v169, 0x4f7ffffe, v169
	v_cvt_u32_f32_e32 v169, v169
	s_nop 0
	v_readfirstlane_b32 s13, v169
	s_mul_i32 s12, s12, s13
	s_mul_hi_u32 s12, s13, s12
	s_add_i32 s13, s13, s12
	s_mul_hi_u32 s12, s6, s13
	s_mul_i32 s13, s12, s4
	s_sub_i32 s6, s6, s13
	s_add_i32 s14, s12, 1
	s_sub_i32 s13, s6, s4
	s_cmp_ge_u32 s6, s4
	s_cselect_b32 s12, s14, s12
	s_cselect_b32 s6, s13, s6
	s_add_i32 s13, s12, 1
	s_cmp_ge_u32 s6, s4
	s_cselect_b32 s4, s13, s12
	s_xor_b32 s4, s4, s7
	s_sub_i32 s4, s4, s7
	s_mul_i32 s5, s4, s5
	s_sub_i32 s5, s62, s5
	s_cmp_lg_u32 s5, 0
	s_ashr_i32 s5, s4, 31
	s_lshl_b64 s[6:7], s[4:5], 13
	v_readlane_b32 s12, v254, 58
	v_readlane_b32 s13, v254, 59
	s_add_u32 s6, s12, s6
	s_addc_u32 s7, s13, s7
	v_mov_b32_e32 v179, 0
	v_lshlrev_b32_e32 v178, 4, v0
	v_lshl_add_u64 v[170:171], s[6:7], 0, v[178:179]
	v_add_co_u32_e32 v172, vcc, 0x40000, v170
	global_load_dwordx4 v[184:187], v178, s[6:7]
	s_nop 0
	v_addc_co_u32_e32 v173, vcc, 0, v171, vcc
	v_add_co_u32_e32 v174, vcc, 0x80000, v170
	s_add_i32 s6, s4, 0x2000
	s_nop 0
	v_addc_co_u32_e32 v175, vcc, 0, v171, vcc
	v_add_co_u32_e32 v170, vcc, 0xc0000, v170
	global_load_dwordx4 v[188:191], v[172:173], off
	global_load_dwordx4 v[192:195], v[174:175], off
	v_addc_co_u32_e32 v171, vcc, 0, v171, vcc
	global_load_dwordx4 v[196:199], v[170:171], off
	s_ashr_i32 s7, s6, 31
	s_lshl_b64 s[4:5], s[6:7], 12
	v_readlane_b32 s12, v254, 54
	v_readlane_b32 s13, v254, 55
	s_add_u32 s4, s12, s4
	s_addc_u32 s5, s13, s5
	v_lshlrev_b32_e32 v182, 3, v0
	global_load_dwordx4 v[174:177], v178, s[8:9]
	global_load_dwordx4 v[170:173], v178, s[10:11]
	global_load_dwordx2 v[180:181], v182, s[4:5]
	s_lshl_b32 s4, s62, 3
	s_add_i32 s12, s4, s96
	s_and_b32 s4, s4, 0xf8
	s_lshl_b32 s5, s62, 5
	s_add_i32 s4, s4, s96
	s_and_b32 s5, s5, 0xfffffc00
	s_add_i32 s13, s4, s5
	s_add_i32 s15, s13, 0x400
	s_cmpk_eq_i32 s90, 0x100
	s_cselect_b64 s[4:5], -1, 0
	s_and_b64 s[6:7], s[4:5], exec
	s_cselect_b32 s14, s13, s12
	s_cselect_b32 s13, s15, 0x2000
	s_cmp_ge_i32 s14, s13
	s_cbranch_scc1 .LBB0_1772
	s_lshl_b32 s6, s90, 3
	v_lshlrev_b32_e32 v1, 5, v166
	s_and_b64 s[4:5], s[4:5], exec
	v_or_b32_e32 v46, 0x800, v1
	v_or_b32_e32 v54, 0x1000, v1
	v_or_b32_e32 v62, 0x1800, v1
	s_cselect_b32 s16, 0x100, s6
	s_ashr_i32 s15, s14, 31
	global_load_dwordx4 v[2:5], v1, s[8:9] offset:16
	global_load_dwordx4 v[6:9], v1, s[8:9]
	global_load_dwordx4 v[10:13], v46, s[8:9] offset:16
	global_load_dwordx4 v[14:17], v46, s[8:9]
	global_load_dwordx4 v[18:21], v54, s[8:9] offset:16
	global_load_dwordx4 v[22:25], v54, s[8:9]
	global_load_dwordx4 v[26:29], v62, s[8:9] offset:16
	global_load_dwordx4 v[30:33], v62, s[8:9]
	global_load_dwordx4 v[34:37], v1, s[10:11] offset:16
	global_load_dwordx4 v[38:41], v1, s[10:11]
	global_load_dwordx4 v[42:45], v46, s[10:11] offset:16
	s_nop 0
	global_load_dwordx4 v[46:49], v46, s[10:11]
	s_nop 0
	global_load_dwordx4 v[50:53], v54, s[10:11] offset:16
	s_nop 0
	global_load_dwordx4 v[54:57], v54, s[10:11]
	s_lshl_b64 s[6:7], s[14:15], 11
	s_lshl_b64 s[20:21], s[14:15], 12
	v_readlane_b32 s4, v254, 54
	v_readlane_b32 s5, v254, 55
	s_add_u32 s4, s4, s20
	s_addc_u32 s5, s5, s21
	s_add_u32 s22, s80, s20
	v_lshlrev_b32_e32 v66, 4, v166
	s_addc_u32 s23, s81, s21
	global_load_dwordx4 v[110:113], v66, s[4:5] nt
	global_load_dwordx4 v[106:109], v66, s[4:5] offset:1024 nt
	global_load_dwordx4 v[102:105], v66, s[4:5] offset:2048 nt
	global_load_dwordx4 v[126:129], v66, s[22:23] nt
	global_load_dwordx4 v[122:125], v66, s[22:23] offset:1024 nt
	global_load_dwordx4 v[98:101], v66, s[4:5] offset:3072 nt
	global_load_dwordx4 v[118:121], v66, s[22:23] offset:2048 nt
	global_load_dwordx4 v[114:117], v66, s[22:23] offset:3072 nt
	global_load_dwordx4 v[58:61], v62, s[10:11] offset:16
	s_nop 0
	global_load_dwordx4 v[62:65], v62, s[10:11]
	v_lshl_or_b32 v130, v166, 3, s6
	v_mov_b32_e32 v131, s7
	s_lshl_b64 s[6:7], s[14:15], 2
	s_add_u32 s15, s6, 0x2ee80000
	s_addc_u32 s39, s7, 0
	s_add_i32 s6, s14, s16
	s_ashr_i32 s7, s6, 31
	s_lshl_b64 s[6:7], s[6:7], 12
	v_or_b32_e32 v132, s20, v66
	s_ashr_i32 s17, s16, 31
	v_or_b32_e32 v134, s6, v66
	v_cmp_eq_u32_e64 s[4:5], 0, v166
	s_mov_b32 s30, 0x2f1e0000
	s_mov_b32 s31, 0x2f1e1000
	v_mov_b32_e32 v1, 0
	v_mov_b32_e32 v136, 0x358637bd
	s_mov_b32 s34, 0x42fe0000
	s_mov_b32 s35, 0xc0c0400
	s_mov_b32 s36, 0xc040100
	s_mov_b32 s37, 0x4020100
	s_mov_b32 s38, 0x2de00000
	v_mov_b32_e32 v137, 0x3a000000
	v_mov_b32_e32 v138, 0x3c010204
	v_mov_b32_e32 v139, 0x42fe0000
	v_mov_b32_e32 v133, s21
	s_lshl_b64 s[20:21], s[16:17], 2
	s_lshl_b64 s[22:23], s[16:17], 11
	s_lshl_b64 s[24:25], s[16:17], 12
	v_mov_b32_e32 v135, s7
	s_waitcnt vmcnt(9)
	v_mov_b64_e32 v[66:67], v[110:111]
	s_waitcnt vmcnt(8)
	v_mov_b64_e32 v[70:71], v[106:107]
	s_waitcnt vmcnt(7)
	v_mov_b64_e32 v[78:79], v[102:103]
	s_waitcnt vmcnt(6)
	v_mov_b64_e32 v[74:75], v[126:127]
	s_waitcnt vmcnt(5)
	v_mov_b64_e32 v[82:83], v[122:123]
	s_waitcnt vmcnt(4)
	v_mov_b64_e32 v[94:95], v[98:99]
	s_waitcnt vmcnt(3)
	v_mov_b64_e32 v[86:87], v[118:119]
	s_waitcnt vmcnt(2)
	v_mov_b64_e32 v[90:91], v[114:115]
	v_mov_b64_e32 v[68:69], v[112:113]
	v_mov_b64_e32 v[72:73], v[108:109]
	v_mov_b64_e32 v[80:81], v[104:105]
	v_mov_b64_e32 v[76:77], v[128:129]
	v_mov_b64_e32 v[84:85], v[124:125]
	v_mov_b64_e32 v[88:89], v[120:121]
	v_mov_b64_e32 v[92:93], v[116:117]
	v_mov_b64_e32 v[96:97], v[100:101]
	s_branch .LBB0_1768

.LBB0_2035:
	s_cmp_lt_i32 s42, 24
	s_cselect_b64 s[4:5], -1, 0
	s_cmp_gt_i32 s43, 23
	s_cselect_b64 s[6:7], -1, 0
	s_and_b64 s[4:5], s[4:5], s[6:7]
	s_andn2_b64 vcc, exec, s[4:5]
	s_cbranch_vccnz .LBB0_2107
	s_load_dwordx16 s[64:79], s[0:1], 0x0
	s_waitcnt lgkmcnt(0)
	s_mov_b64 s[12:13], s[76:77]
	s_mov_b64 s[14:15], s[78:79]
	s_add_u32 s4, s14, 0x1a000
	s_addc_u32 s5, s15, 0
	s_add_u32 s6, s14, 0x1c000
	s_addc_u32 s7, s15, 0
	s_ashr_i32 s9, s90, 5
	s_abs_i32 s8, s9
	v_cvt_f32_u32_e32 v169, s8
	s_sub_i32 s12, 0, s8
	s_abs_i32 s10, s62
	s_xor_b32 s11, s62, s9
	v_rcp_iflag_f32_e32 v169, v169
	s_ashr_i32 s11, s11, 31
	v_mul_f32_e32 v169, 0x4f7ffffe, v169
	v_cvt_u32_f32_e32 v169, v169
	s_nop 0
	v_readfirstlane_b32 s13, v169
	s_mul_i32 s12, s12, s13
	s_mul_hi_u32 s12, s13, s12
	s_add_i32 s13, s13, s12
	s_mul_hi_u32 s12, s10, s13
	s_mul_i32 s13, s12, s8
	s_sub_i32 s10, s10, s13
	s_add_i32 s14, s12, 1
	s_sub_i32 s13, s10, s8
	s_cmp_ge_u32 s10, s8
	s_cselect_b32 s12, s14, s12
	s_cselect_b32 s10, s13, s10
	s_add_i32 s13, s12, 1
	s_cmp_ge_u32 s10, s8
	s_cselect_b32 s8, s13, s12
	s_xor_b32 s8, s8, s11
	s_sub_i32 s8, s8, s11
	s_mul_i32 s9, s8, s9
	s_sub_i32 s9, s62, s9
	s_cmp_lg_u32 s9, 0
	s_ashr_i32 s9, s8, 31
	s_lshl_b64 s[10:11], s[8:9], 13
	v_readlane_b32 s12, v254, 58
	v_readlane_b32 s13, v254, 59
	s_add_u32 s10, s12, s10
	s_addc_u32 s11, s13, s11
	v_mov_b32_e32 v181, 0
	v_lshlrev_b32_e32 v180, 4, v0
	v_lshl_add_u64 v[170:171], s[10:11], 0, v[180:181]
	v_add_co_u32_e32 v172, vcc, 0x40000, v170
	global_load_dwordx4 v[186:189], v180, s[10:11]
	s_nop 0
	v_addc_co_u32_e32 v173, vcc, 0, v171, vcc
	v_add_co_u32_e32 v174, vcc, 0x80000, v170
	s_addk_i32 s8, 0x2000
	s_nop 0
	v_addc_co_u32_e32 v175, vcc, 0, v171, vcc
	v_add_co_u32_e32 v170, vcc, 0xc0000, v170
	global_load_dwordx4 v[190:193], v[172:173], off
	global_load_dwordx4 v[194:197], v[174:175], off
	v_addc_co_u32_e32 v171, vcc, 0, v171, vcc
	global_load_dwordx4 v[198:201], v[170:171], off
	s_ashr_i32 s9, s8, 31
	s_lshl_b64 s[10:11], s[8:9], 12
	v_readlane_b32 s12, v254, 54
	v_readlane_b32 s13, v254, 55
	s_add_u32 s10, s12, s10
	s_addc_u32 s11, s13, s11
	v_lshlrev_b32_e32 v178, 3, v0
	global_load_dwordx4 v[174:177], v180, s[4:5]
	global_load_dwordx4 v[170:173], v180, s[6:7]
	global_load_dwordx2 v[182:183], v178, s[10:11]
	s_lshl_b32 s9, s62, 3
	s_add_i32 s8, s9, s96
	s_and_b32 s9, s9, 0xf8
	s_lshl_b32 s10, s62, 5
	s_add_i32 s9, s9, s96
	s_and_b32 s10, s10, 0xfffffc00
	s_add_i32 s9, s9, s10
	s_add_i32 s14, s9, 0x400
	s_cmpk_eq_i32 s90, 0x100
	s_cselect_b64 s[12:13], -1, 0
	s_and_b64 s[10:11], s[12:13], exec
	s_cselect_b32 s10, s9, s8
	s_cselect_b32 s9, s14, 0x2000
	s_cmp_ge_i32 s10, s9
	s_cbranch_scc1 .LBB0_2041
	s_lshl_b32 s11, s90, 3
	v_lshlrev_b32_e32 v1, 5, v166
	s_and_b64 s[12:13], s[12:13], exec
	v_or_b32_e32 v46, 0x800, v1
	v_or_b32_e32 v54, 0x1000, v1
	v_or_b32_e32 v62, 0x1800, v1
	s_cselect_b32 s12, 0x100, s11
	s_ashr_i32 s11, s10, 31
	global_load_dwordx4 v[2:5], v1, s[4:5] offset:16
	global_load_dwordx4 v[6:9], v1, s[4:5]
	global_load_dwordx4 v[10:13], v46, s[4:5] offset:16
	global_load_dwordx4 v[14:17], v46, s[4:5]
	global_load_dwordx4 v[18:21], v54, s[4:5] offset:16
	global_load_dwordx4 v[22:25], v54, s[4:5]
	global_load_dwordx4 v[26:29], v62, s[4:5] offset:16
	global_load_dwordx4 v[30:33], v62, s[4:5]
	global_load_dwordx4 v[34:37], v1, s[6:7] offset:16
	global_load_dwordx4 v[38:41], v1, s[6:7]
	global_load_dwordx4 v[42:45], v46, s[6:7] offset:16
	s_nop 0
	global_load_dwordx4 v[46:49], v46, s[6:7]
	s_nop 0
	global_load_dwordx4 v[50:53], v54, s[6:7] offset:16
	s_nop 0
	global_load_dwordx4 v[54:57], v54, s[6:7]
	s_lshl_b64 s[14:15], s[10:11], 12
	v_readlane_b32 s16, v254, 54
	v_readlane_b32 s17, v254, 55
	s_add_u32 s16, s16, s14
	s_addc_u32 s17, s17, s15
	s_add_u32 s20, s80, s14
	v_lshlrev_b32_e32 v130, 4, v166
	s_addc_u32 s21, s81, s15
	global_load_dwordx4 v[110:113], v130, s[16:17] nt
	global_load_dwordx4 v[106:109], v130, s[16:17] offset:1024 nt
	global_load_dwordx4 v[102:105], v130, s[16:17] offset:2048 nt
	global_load_dwordx4 v[126:129], v130, s[20:21] nt
	global_load_dwordx4 v[122:125], v130, s[20:21] offset:1024 nt
	global_load_dwordx4 v[98:101], v130, s[16:17] offset:3072 nt
	global_load_dwordx4 v[118:121], v130, s[20:21] offset:2048 nt
	global_load_dwordx4 v[114:117], v130, s[20:21] offset:3072 nt
	global_load_dwordx4 v[58:61], v62, s[6:7] offset:16
	s_nop 0
	global_load_dwordx4 v[62:65], v62, s[6:7]
	s_add_u32 s14, s94, s14
	s_addc_u32 s15, s95, s15
	s_add_i32 s20, s10, s12
	s_ashr_i32 s13, s12, 31
	s_ashr_i32 s21, s20, 31
	s_lshl_b64 s[16:17], s[12:13], 12
	s_lshl_b64 s[20:21], s[20:21], 12
	s_add_u32 s20, s94, s20
	v_mov_b32_e32 v131, 0
	s_mov_b32 s11, 0x2f1e0000
	s_mov_b32 s24, 0x2f1e1000
	v_mov_b32_e32 v1, 0x358637bd
	s_mov_b32 s25, 0x1b500000
	v_mov_b32_e32 v132, 0x3a000000
	s_addc_u32 s21, s95, s21
	s_waitcnt vmcnt(9)
	v_mov_b64_e32 v[66:67], v[110:111]
	s_waitcnt vmcnt(8)
	v_mov_b64_e32 v[70:71], v[106:107]
	s_waitcnt vmcnt(7)
	v_mov_b64_e32 v[78:79], v[102:103]
	s_waitcnt vmcnt(6)
	v_mov_b64_e32 v[74:75], v[126:127]
	s_waitcnt vmcnt(5)
	v_mov_b64_e32 v[82:83], v[122:123]
	s_waitcnt vmcnt(4)
	v_mov_b64_e32 v[94:95], v[98:99]
	s_waitcnt vmcnt(3)
	v_mov_b64_e32 v[86:87], v[118:119]
	s_waitcnt vmcnt(2)
	v_mov_b64_e32 v[90:91], v[114:115]
	v_mov_b64_e32 v[68:69], v[112:113]
	v_mov_b64_e32 v[72:73], v[108:109]
	v_mov_b64_e32 v[80:81], v[104:105]
	v_mov_b64_e32 v[76:77], v[128:129]
	v_mov_b64_e32 v[84:85], v[124:125]
	v_mov_b64_e32 v[88:89], v[120:121]
	v_mov_b64_e32 v[92:93], v[116:117]
	v_mov_b64_e32 v[96:97], v[100:101]
	s_branch .LBB0_2039

.LBB0_2368:
	s_cmp_lt_i32 s42, 27
	s_cselect_b64 s[0:1], -1, 0
	s_cmp_gt_i32 s43, 26
	s_cselect_b64 s[4:5], -1, 0
	s_and_b64 s[0:1], s[0:1], s[4:5]
	s_andn2_b64 vcc, exec, s[0:1]
	s_cbranch_vccnz .LBB0_2448
	v_readlane_b32 s64, v254, 2
	v_readlane_b32 s78, v254, 16
	v_readlane_b32 s79, v254, 17
	s_mov_b64 s[14:15], s[78:79]
	s_add_u32 s6, s14, 0x1e000
	s_addc_u32 s7, s15, 0
	s_add_u32 s8, s14, 0x20000
	s_addc_u32 s9, s15, 0
	s_ashr_i32 s1, s90, 5
	s_abs_i32 s0, s1
	v_cvt_f32_u32_e32 v175, s0
	s_sub_i32 s10, 0, s0
	s_abs_i32 s4, s62
	s_xor_b32 s5, s62, s1
	v_rcp_iflag_f32_e32 v175, v175
	s_ashr_i32 s5, s5, 31
	v_mul_f32_e32 v175, 0x4f7ffffe, v175
	v_cvt_u32_f32_e32 v175, v175
	s_nop 0
	v_readfirstlane_b32 s11, v175
	s_mul_i32 s10, s10, s11
	s_mul_hi_u32 s10, s11, s10
	s_add_i32 s11, s11, s10
	s_mul_hi_u32 s10, s4, s11
	s_mul_i32 s11, s10, s0
	s_sub_i32 s4, s4, s11
	s_add_i32 s12, s10, 1
	s_sub_i32 s11, s4, s0
	s_cmp_ge_u32 s4, s0
	s_cselect_b32 s10, s12, s10
	s_cselect_b32 s4, s11, s4
	s_add_i32 s11, s10, 1
	s_cmp_ge_u32 s4, s0
	s_cselect_b32 s0, s11, s10
	s_xor_b32 s0, s0, s5
	s_sub_i32 s0, s0, s5
	s_mul_i32 s1, s0, s1
	s_sub_i32 s1, s62, s1
	s_cmp_lg_u32 s1, 0
	s_ashr_i32 s1, s0, 31
	s_lshl_b64 s[4:5], s[0:1], 13
	v_readlane_b32 s10, v254, 58
	v_readlane_b32 s11, v254, 59
	s_add_u32 s4, s10, s4
	s_addc_u32 s5, s11, s5
	v_mov_b32_e32 v185, 0
	v_lshlrev_b32_e32 v184, 4, v0
	v_lshl_add_u64 v[176:177], s[4:5], 0, v[184:185]
	v_add_co_u32_e32 v178, vcc, 0x40000, v176
	global_load_dwordx4 v[190:193], v184, s[4:5]
	s_nop 0
	v_addc_co_u32_e32 v179, vcc, 0, v177, vcc
	v_add_co_u32_e32 v180, vcc, 0x80000, v176
	s_add_i32 s4, s0, 0x2000
	s_nop 0
	v_addc_co_u32_e32 v181, vcc, 0, v177, vcc
	v_add_co_u32_e32 v176, vcc, 0xc0000, v176
	s_ashr_i32 s5, s4, 31
	s_nop 0
	v_addc_co_u32_e32 v177, vcc, 0, v177, vcc
	global_load_dwordx4 v[194:197], v[178:179], off
	global_load_dwordx4 v[198:201], v[180:181], off
	global_load_dwordx4 v[202:205], v[176:177], off
	s_lshl_b64 s[0:1], s[4:5], 12
	v_readlane_b32 s10, v254, 54
	v_readlane_b32 s11, v254, 55
	s_add_u32 s10, s10, s0
	s_addc_u32 s11, s11, s1
	s_add_u32 s0, s84, s0
	v_readlane_b32 s64, v254, 18
	v_lshlrev_b32_e32 v188, 3, v0
	s_addc_u32 s1, s85, s1
	v_readlane_b32 s66, v254, 20
	v_readlane_b32 s67, v254, 21
	global_load_dwordx2 v[210:211], v188, s[0:1]
	s_nop 3
	global_load_dwordx4 v[206:209], v184, s[66:67]
	global_load_dwordx4 v[180:183], v184, s[6:7]
	global_load_dwordx4 v[176:179], v184, s[8:9]
	global_load_dwordx2 v[186:187], v188, s[10:11]
	s_lshl_b32 s0, s62, 3
	s_add_i32 s10, s0, s96
	s_and_b32 s0, s0, 0xf8
	s_lshl_b32 s1, s62, 5
	s_add_i32 s0, s0, s96
	s_and_b32 s1, s1, 0xfffffc00
	s_add_i32 s11, s0, s1
	s_add_i32 s13, s11, 0x400
	s_cmpk_eq_i32 s90, 0x100
	s_cselect_b64 s[0:1], -1, 0
	s_and_b64 s[4:5], s[0:1], exec
	s_cselect_b32 s12, s11, s10
	s_cselect_b32 s11, s13, 0x2000
	s_cmp_ge_i32 s12, s11
	v_readlane_b32 s65, v254, 3
	v_readlane_b32 s66, v254, 4
	v_readlane_b32 s67, v254, 5
	v_readlane_b32 s68, v254, 6
	v_readlane_b32 s69, v254, 7
	v_readlane_b32 s70, v254, 8
	v_readlane_b32 s71, v254, 9
	v_readlane_b32 s72, v254, 10
	v_readlane_b32 s73, v254, 11
	v_readlane_b32 s74, v254, 12
	v_readlane_b32 s75, v254, 13
	v_readlane_b32 s76, v254, 14
	v_readlane_b32 s77, v254, 15
	s_cbranch_scc1 .LBB0_2376
	s_lshl_b32 s4, s90, 3
	v_lshlrev_b32_e32 v1, 5, v166
	s_and_b64 s[0:1], s[0:1], exec
	v_or_b32_e32 v46, 0x800, v1
	v_or_b32_e32 v54, 0x1000, v1
	v_or_b32_e32 v62, 0x1800, v1
	s_cselect_b32 s14, 0x100, s4
	s_ashr_i32 s13, s12, 31
	global_load_dwordx4 v[2:5], v1, s[6:7] offset:16
	global_load_dwordx4 v[6:9], v1, s[6:7]
	global_load_dwordx4 v[10:13], v46, s[6:7] offset:16
	global_load_dwordx4 v[14:17], v46, s[6:7]
	global_load_dwordx4 v[18:21], v54, s[6:7] offset:16
	global_load_dwordx4 v[22:25], v54, s[6:7]
	global_load_dwordx4 v[26:29], v62, s[6:7] offset:16
	global_load_dwordx4 v[30:33], v62, s[6:7]
	global_load_dwordx4 v[34:37], v1, s[8:9] offset:16
	global_load_dwordx4 v[38:41], v1, s[8:9]
	global_load_dwordx4 v[42:45], v46, s[8:9] offset:16
	s_nop 0
	global_load_dwordx4 v[46:49], v46, s[8:9]
	s_nop 0
	global_load_dwordx4 v[50:53], v54, s[8:9] offset:16
	s_nop 0
	global_load_dwordx4 v[54:57], v54, s[8:9]
	s_lshl_b64 s[4:5], s[12:13], 11
	s_lshl_b64 s[16:17], s[12:13], 12
	v_readlane_b32 s0, v254, 54
	v_readlane_b32 s1, v254, 55
	s_add_u32 s0, s0, s16
	s_addc_u32 s1, s1, s17
	s_add_u32 s20, s80, s16
	v_lshlrev_b32_e32 v66, 4, v166
	s_addc_u32 s21, s81, s17
	global_load_dwordx4 v[110:113], v66, s[0:1] nt
	global_load_dwordx4 v[106:109], v66, s[0:1] offset:1024 nt
	global_load_dwordx4 v[102:105], v66, s[0:1] offset:2048 nt
	global_load_dwordx4 v[126:129], v66, s[20:21] nt
	global_load_dwordx4 v[122:125], v66, s[20:21] offset:1024 nt
	global_load_dwordx4 v[98:101], v66, s[0:1] offset:3072 nt
	global_load_dwordx4 v[118:121], v66, s[20:21] offset:2048 nt
	global_load_dwordx4 v[114:117], v66, s[20:21] offset:3072 nt
	global_load_dwordx4 v[58:61], v62, s[8:9] offset:16
	s_nop 0
	global_load_dwordx4 v[62:65], v62, s[8:9]
	v_lshl_or_b32 v130, v166, 3, s4
	v_mov_b32_e32 v131, s5
	s_lshl_b64 s[4:5], s[12:13], 2
	s_add_u32 s13, s4, 0x2ee80000
	s_addc_u32 s37, s5, 0
	s_add_i32 s4, s12, s14
	s_ashr_i32 s5, s4, 31
	s_lshl_b64 s[4:5], s[4:5], 12
	v_or_b32_e32 v132, s16, v66
	s_ashr_i32 s15, s14, 31
	v_or_b32_e32 v134, s4, v66
	v_cmp_eq_u32_e64 s[0:1], 0, v166
	s_mov_b32 s28, 0x2f1e0000
	s_mov_b32 s29, 0x2f1e1000
	v_mov_b32_e32 v1, 0
	v_mov_b32_e32 v136, 0x358637bd
	s_mov_b32 s30, 0x42fe0000
	s_mov_b32 s31, 0xc0c0400
	s_mov_b32 s34, 0xc040100
	s_mov_b32 s35, 0x4020100
	s_mov_b32 s36, 0x2de00000
	v_mov_b32_e32 v137, 0x3a000000
	v_mov_b32_e32 v138, 0x3c010204
	v_mov_b32_e32 v139, 0x42fe0000
	v_mov_b32_e32 v133, s17
	s_lshl_b64 s[16:17], s[14:15], 2
	s_lshl_b64 s[20:21], s[14:15], 11
	s_lshl_b64 s[22:23], s[14:15], 12
	v_mov_b32_e32 v135, s5
	s_waitcnt vmcnt(9)
	v_mov_b64_e32 v[66:67], v[110:111]
	s_waitcnt vmcnt(8)
	v_mov_b64_e32 v[70:71], v[106:107]
	s_waitcnt vmcnt(7)
	v_mov_b64_e32 v[78:79], v[102:103]
	s_waitcnt vmcnt(6)
	v_mov_b64_e32 v[74:75], v[126:127]
	s_waitcnt vmcnt(5)
	v_mov_b64_e32 v[82:83], v[122:123]
	s_waitcnt vmcnt(4)
	v_mov_b64_e32 v[94:95], v[98:99]
	s_waitcnt vmcnt(3)
	v_mov_b64_e32 v[86:87], v[118:119]
	s_waitcnt vmcnt(2)
	v_mov_b64_e32 v[90:91], v[114:115]
	v_mov_b64_e32 v[68:69], v[112:113]
	v_mov_b64_e32 v[72:73], v[108:109]
	v_mov_b64_e32 v[80:81], v[104:105]
	v_mov_b64_e32 v[76:77], v[128:129]
	v_mov_b64_e32 v[84:85], v[124:125]
	v_mov_b64_e32 v[88:89], v[120:121]
	v_mov_b64_e32 v[92:93], v[116:117]
	v_mov_b64_e32 v[96:97], v[100:101]
	s_branch .LBB0_2372

.LBB0_2639:
	s_cmp_lt_i32 s42, 30
	s_cselect_b64 s[0:1], -1, 0
	s_cmp_gt_i32 s43, 29
	s_cselect_b64 s[4:5], -1, 0
	s_and_b64 s[0:1], s[0:1], s[4:5]
	s_andn2_b64 vcc, exec, s[0:1]
	s_cbranch_vccnz .LBB0_2719
	v_readlane_b32 s64, v254, 2
	v_readlane_b32 s78, v254, 16
	v_readlane_b32 s79, v254, 17
	s_mov_b64 s[14:15], s[78:79]
	s_add_u32 s6, s14, 0x22000
	s_addc_u32 s7, s15, 0
	s_add_u32 s8, s14, 0x24000
	s_addc_u32 s9, s15, 0
	s_ashr_i32 s1, s90, 5
	s_abs_i32 s0, s1
	v_cvt_f32_u32_e32 v169, s0
	s_sub_i32 s10, 0, s0
	s_abs_i32 s4, s62
	s_xor_b32 s5, s62, s1
	v_rcp_iflag_f32_e32 v169, v169
	s_ashr_i32 s5, s5, 31
	v_mul_f32_e32 v169, 0x4f7ffffe, v169
	v_cvt_u32_f32_e32 v169, v169
	s_nop 0
	v_readfirstlane_b32 s11, v169
	s_mul_i32 s10, s10, s11
	s_mul_hi_u32 s10, s11, s10
	s_add_i32 s11, s11, s10
	s_mul_hi_u32 s10, s4, s11
	s_mul_i32 s11, s10, s0
	s_sub_i32 s4, s4, s11
	s_add_i32 s12, s10, 1
	s_sub_i32 s11, s4, s0
	s_cmp_ge_u32 s4, s0
	s_cselect_b32 s10, s12, s10
	s_cselect_b32 s4, s11, s4
	s_add_i32 s11, s10, 1
	s_cmp_ge_u32 s4, s0
	s_cselect_b32 s0, s11, s10
	s_xor_b32 s0, s0, s5
	s_sub_i32 s0, s0, s5
	s_mul_i32 s1, s0, s1
	s_sub_i32 s1, s62, s1
	s_cmp_lg_u32 s1, 0
	s_ashr_i32 s1, s0, 31
	s_lshl_b64 s[4:5], s[0:1], 13
	v_readlane_b32 s10, v254, 58
	v_readlane_b32 s11, v254, 59
	s_add_u32 s4, s10, s4
	s_addc_u32 s5, s11, s5
	v_mov_b32_e32 v179, 0
	v_lshlrev_b32_e32 v178, 4, v0
	v_lshl_add_u64 v[170:171], s[4:5], 0, v[178:179]
	v_add_co_u32_e32 v172, vcc, 0x40000, v170
	global_load_dwordx4 v[184:187], v178, s[4:5]
	s_nop 0
	v_addc_co_u32_e32 v173, vcc, 0, v171, vcc
	v_add_co_u32_e32 v174, vcc, 0x80000, v170
	s_add_i32 s4, s0, 0x2000
	s_nop 0
	v_addc_co_u32_e32 v175, vcc, 0, v171, vcc
	v_add_co_u32_e32 v170, vcc, 0xc0000, v170
	global_load_dwordx4 v[188:191], v[172:173], off
	global_load_dwordx4 v[192:195], v[174:175], off
	v_addc_co_u32_e32 v171, vcc, 0, v171, vcc
	global_load_dwordx4 v[196:199], v[170:171], off
	s_ashr_i32 s5, s4, 31
	s_lshl_b64 s[0:1], s[4:5], 12
	v_readlane_b32 s10, v254, 54
	v_readlane_b32 s11, v254, 55
	s_add_u32 s0, s10, s0
	s_addc_u32 s1, s11, s1
	v_lshlrev_b32_e32 v182, 3, v0
	global_load_dwordx4 v[174:177], v178, s[6:7]
	global_load_dwordx4 v[170:173], v178, s[8:9]
	global_load_dwordx2 v[180:181], v182, s[0:1]
	s_lshl_b32 s0, s62, 3
	s_add_i32 s10, s0, s96
	s_and_b32 s0, s0, 0xf8
	s_lshl_b32 s1, s62, 5
	s_add_i32 s0, s0, s96
	s_and_b32 s1, s1, 0xfffffc00
	s_add_i32 s11, s0, s1
	s_add_i32 s13, s11, 0x400
	s_cmpk_eq_i32 s90, 0x100
	s_cselect_b64 s[0:1], -1, 0
	s_and_b64 s[4:5], s[0:1], exec
	s_cselect_b32 s12, s11, s10
	s_cselect_b32 s11, s13, 0x2000
	s_cmp_ge_i32 s12, s11
	v_readlane_b32 s65, v254, 3
	v_readlane_b32 s66, v254, 4
	v_readlane_b32 s67, v254, 5
	v_readlane_b32 s68, v254, 6
	v_readlane_b32 s69, v254, 7
	v_readlane_b32 s70, v254, 8
	v_readlane_b32 s71, v254, 9
	v_readlane_b32 s72, v254, 10
	v_readlane_b32 s73, v254, 11
	v_readlane_b32 s74, v254, 12
	v_readlane_b32 s75, v254, 13
	v_readlane_b32 s76, v254, 14
	v_readlane_b32 s77, v254, 15
	s_cbranch_scc1 .LBB0_2647
	s_lshl_b32 s4, s90, 3
	v_lshlrev_b32_e32 v1, 5, v166
	s_and_b64 s[0:1], s[0:1], exec
	v_or_b32_e32 v46, 0x800, v1
	v_or_b32_e32 v54, 0x1000, v1
	v_or_b32_e32 v62, 0x1800, v1
	s_cselect_b32 s14, 0x100, s4
	s_ashr_i32 s13, s12, 31
	global_load_dwordx4 v[2:5], v1, s[6:7] offset:16
	global_load_dwordx4 v[6:9], v1, s[6:7]
	global_load_dwordx4 v[10:13], v46, s[6:7] offset:16
	global_load_dwordx4 v[14:17], v46, s[6:7]
	global_load_dwordx4 v[18:21], v54, s[6:7] offset:16
	global_load_dwordx4 v[22:25], v54, s[6:7]
	global_load_dwordx4 v[26:29], v62, s[6:7] offset:16
	global_load_dwordx4 v[30:33], v62, s[6:7]
	global_load_dwordx4 v[34:37], v1, s[8:9] offset:16
	global_load_dwordx4 v[38:41], v1, s[8:9]
	global_load_dwordx4 v[42:45], v46, s[8:9] offset:16
	s_nop 0
	global_load_dwordx4 v[46:49], v46, s[8:9]
	s_nop 0
	global_load_dwordx4 v[50:53], v54, s[8:9] offset:16
	s_nop 0
	global_load_dwordx4 v[54:57], v54, s[8:9]
	s_lshl_b64 s[4:5], s[12:13], 11
	s_lshl_b64 s[16:17], s[12:13], 12
	v_readlane_b32 s0, v254, 54
	v_readlane_b32 s1, v254, 55
	s_add_u32 s0, s0, s16
	s_addc_u32 s1, s1, s17
	s_add_u32 s20, s80, s16
	v_lshlrev_b32_e32 v66, 4, v166
	s_addc_u32 s21, s81, s17
	global_load_dwordx4 v[110:113], v66, s[0:1] nt
	global_load_dwordx4 v[106:109], v66, s[0:1] offset:1024 nt
	global_load_dwordx4 v[102:105], v66, s[0:1] offset:2048 nt
	global_load_dwordx4 v[126:129], v66, s[20:21] nt
	global_load_dwordx4 v[122:125], v66, s[20:21] offset:1024 nt
	global_load_dwordx4 v[98:101], v66, s[0:1] offset:3072 nt
	global_load_dwordx4 v[118:121], v66, s[20:21] offset:2048 nt
	global_load_dwordx4 v[114:117], v66, s[20:21] offset:3072 nt
	global_load_dwordx4 v[58:61], v62, s[8:9] offset:16
	s_nop 0
	global_load_dwordx4 v[62:65], v62, s[8:9]
	v_lshl_or_b32 v130, v166, 3, s4
	v_mov_b32_e32 v131, s5
	s_lshl_b64 s[4:5], s[12:13], 2
	s_add_u32 s13, s4, 0x2ee80000
	s_addc_u32 s37, s5, 0
	s_add_i32 s4, s12, s14
	s_ashr_i32 s5, s4, 31
	s_lshl_b64 s[4:5], s[4:5], 12
	v_or_b32_e32 v132, s16, v66
	s_ashr_i32 s15, s14, 31
	v_or_b32_e32 v134, s4, v66
	v_cmp_eq_u32_e64 s[0:1], 0, v166
	s_mov_b32 s28, 0x2f1e0000
	s_mov_b32 s29, 0x2f1e1000
	v_mov_b32_e32 v1, 0
	v_mov_b32_e32 v136, 0x358637bd
	s_mov_b32 s30, 0x42fe0000
	s_mov_b32 s31, 0xc0c0400
	s_mov_b32 s34, 0xc040100
	s_mov_b32 s35, 0x4020100
	s_mov_b32 s36, 0x2de00000
	v_mov_b32_e32 v137, 0x3a000000
	v_mov_b32_e32 v138, 0x3c010204
	v_mov_b32_e32 v139, 0x42fe0000
	v_mov_b32_e32 v133, s17
	s_lshl_b64 s[16:17], s[14:15], 2
	s_lshl_b64 s[20:21], s[14:15], 11
	s_lshl_b64 s[22:23], s[14:15], 12
	v_mov_b32_e32 v135, s5
	s_waitcnt vmcnt(9)
	v_mov_b64_e32 v[66:67], v[110:111]
	s_waitcnt vmcnt(8)
	v_mov_b64_e32 v[70:71], v[106:107]
	s_waitcnt vmcnt(7)
	v_mov_b64_e32 v[78:79], v[102:103]
	s_waitcnt vmcnt(6)
	v_mov_b64_e32 v[74:75], v[126:127]
	s_waitcnt vmcnt(5)
	v_mov_b64_e32 v[82:83], v[122:123]
	s_waitcnt vmcnt(4)
	v_mov_b64_e32 v[94:95], v[98:99]
	s_waitcnt vmcnt(3)
	v_mov_b64_e32 v[86:87], v[118:119]
	s_waitcnt vmcnt(2)
	v_mov_b64_e32 v[90:91], v[114:115]
	v_mov_b64_e32 v[68:69], v[112:113]
	v_mov_b64_e32 v[72:73], v[108:109]
	v_mov_b64_e32 v[80:81], v[104:105]
	v_mov_b64_e32 v[76:77], v[128:129]
	v_mov_b64_e32 v[84:85], v[124:125]
	v_mov_b64_e32 v[88:89], v[120:121]
	v_mov_b64_e32 v[92:93], v[116:117]
	v_mov_b64_e32 v[96:97], v[100:101]
	s_branch .LBB0_2643

.LBB0_2910:
	s_cmp_lt_i32 s42, 33
	s_cselect_b64 s[0:1], -1, 0
	s_cmp_gt_i32 s43, 32
	s_cselect_b64 s[4:5], -1, 0
	s_and_b64 s[0:1], s[0:1], s[4:5]
	s_andn2_b64 vcc, exec, s[0:1]
	s_cbranch_vccnz .LBB0_2982
	v_readlane_b32 s64, v254, 2
	v_readlane_b32 s78, v254, 16
	v_readlane_b32 s79, v254, 17
	s_mov_b64 s[14:15], s[78:79]
	s_add_u32 s0, s14, 0x26000
	s_addc_u32 s1, s15, 0
	s_add_u32 s4, s14, 0x28000
	s_addc_u32 s5, s15, 0
	s_ashr_i32 s7, s90, 5
	s_abs_i32 s6, s7
	v_cvt_f32_u32_e32 v169, s6
	s_sub_i32 s10, 0, s6
	s_abs_i32 s8, s62
	s_xor_b32 s9, s62, s7
	v_rcp_iflag_f32_e32 v169, v169
	s_ashr_i32 s9, s9, 31
	v_mul_f32_e32 v169, 0x4f7ffffe, v169
	v_cvt_u32_f32_e32 v169, v169
	s_nop 0
	v_readfirstlane_b32 s11, v169
	s_mul_i32 s10, s10, s11
	s_mul_hi_u32 s10, s11, s10
	s_add_i32 s11, s11, s10
	s_mul_hi_u32 s10, s8, s11
	s_mul_i32 s11, s10, s6
	s_sub_i32 s8, s8, s11
	s_add_i32 s12, s10, 1
	s_sub_i32 s11, s8, s6
	s_cmp_ge_u32 s8, s6
	s_cselect_b32 s10, s12, s10
	s_cselect_b32 s8, s11, s8
	s_add_i32 s11, s10, 1
	s_cmp_ge_u32 s8, s6
	s_cselect_b32 s6, s11, s10
	s_xor_b32 s6, s6, s9
	s_sub_i32 s6, s6, s9
	s_mul_i32 s7, s6, s7
	s_sub_i32 s7, s62, s7
	s_cmp_lg_u32 s7, 0
	s_ashr_i32 s7, s6, 31
	s_lshl_b64 s[8:9], s[6:7], 13
	v_readlane_b32 s10, v254, 58
	v_readlane_b32 s11, v254, 59
	s_add_u32 s8, s10, s8
	s_addc_u32 s9, s11, s9
	v_mov_b32_e32 v181, 0
	v_lshlrev_b32_e32 v180, 4, v0
	v_lshl_add_u64 v[170:171], s[8:9], 0, v[180:181]
	v_add_co_u32_e32 v172, vcc, 0x40000, v170
	global_load_dwordx4 v[186:189], v180, s[8:9]
	s_nop 0
	v_addc_co_u32_e32 v173, vcc, 0, v171, vcc
	v_add_co_u32_e32 v174, vcc, 0x80000, v170
	s_addk_i32 s6, 0x2000
	s_nop 0
	v_addc_co_u32_e32 v175, vcc, 0, v171, vcc
	v_add_co_u32_e32 v170, vcc, 0xc0000, v170
	global_load_dwordx4 v[190:193], v[172:173], off
	global_load_dwordx4 v[194:197], v[174:175], off
	v_addc_co_u32_e32 v171, vcc, 0, v171, vcc
	global_load_dwordx4 v[198:201], v[170:171], off
	s_ashr_i32 s7, s6, 31
	s_lshl_b64 s[8:9], s[6:7], 12
	v_readlane_b32 s10, v254, 54
	v_readlane_b32 s11, v254, 55
	s_add_u32 s8, s10, s8
	s_addc_u32 s9, s11, s9
	v_lshlrev_b32_e32 v178, 3, v0
	global_load_dwordx4 v[174:177], v180, s[0:1]
	global_load_dwordx4 v[170:173], v180, s[4:5]
	global_load_dwordx2 v[182:183], v178, s[8:9]
	s_lshl_b32 s7, s62, 3
	s_add_i32 s6, s7, s96
	s_and_b32 s7, s7, 0xf8
	s_lshl_b32 s8, s62, 5
	s_add_i32 s7, s7, s96
	s_and_b32 s8, s8, 0xfffffc00
	s_add_i32 s7, s7, s8
	s_add_i32 s12, s7, 0x400
	s_cmpk_eq_i32 s90, 0x100
	s_cselect_b64 s[10:11], -1, 0
	s_and_b64 s[8:9], s[10:11], exec
	s_cselect_b32 s8, s7, s6
	s_cselect_b32 s7, s12, 0x2000
	s_cmp_ge_i32 s8, s7
	v_readlane_b32 s65, v254, 3
	v_readlane_b32 s66, v254, 4
	v_readlane_b32 s67, v254, 5
	v_readlane_b32 s68, v254, 6
	v_readlane_b32 s69, v254, 7
	v_readlane_b32 s70, v254, 8
	v_readlane_b32 s71, v254, 9
	v_readlane_b32 s72, v254, 10
	v_readlane_b32 s73, v254, 11
	v_readlane_b32 s74, v254, 12
	v_readlane_b32 s75, v254, 13
	v_readlane_b32 s76, v254, 14
	v_readlane_b32 s77, v254, 15
	s_cbranch_scc1 .LBB0_2916
	s_lshl_b32 s9, s90, 3
	v_lshlrev_b32_e32 v1, 5, v166
	s_and_b64 s[10:11], s[10:11], exec
	v_or_b32_e32 v46, 0x800, v1
	v_or_b32_e32 v54, 0x1000, v1
	v_or_b32_e32 v62, 0x1800, v1
	s_cselect_b32 s10, 0x100, s9
	s_ashr_i32 s9, s8, 31
	global_load_dwordx4 v[2:5], v1, s[0:1] offset:16
	global_load_dwordx4 v[6:9], v1, s[0:1]
	global_load_dwordx4 v[10:13], v46, s[0:1] offset:16
	global_load_dwordx4 v[14:17], v46, s[0:1]
	global_load_dwordx4 v[18:21], v54, s[0:1] offset:16
	global_load_dwordx4 v[22:25], v54, s[0:1]
	global_load_dwordx4 v[26:29], v62, s[0:1] offset:16
	global_load_dwordx4 v[30:33], v62, s[0:1]
	global_load_dwordx4 v[34:37], v1, s[4:5] offset:16
	global_load_dwordx4 v[38:41], v1, s[4:5]
	global_load_dwordx4 v[42:45], v46, s[4:5] offset:16
	s_nop 0
	global_load_dwordx4 v[46:49], v46, s[4:5]
	s_nop 0
	global_load_dwordx4 v[50:53], v54, s[4:5] offset:16
	s_nop 0
	global_load_dwordx4 v[54:57], v54, s[4:5]
	s_lshl_b64 s[12:13], s[8:9], 12
	v_readlane_b32 s14, v254, 54
	v_readlane_b32 s15, v254, 55
	s_add_u32 s14, s14, s12
	s_addc_u32 s15, s15, s13
	s_add_u32 s16, s80, s12
	v_lshlrev_b32_e32 v130, 4, v166
	s_addc_u32 s17, s81, s13
	global_load_dwordx4 v[110:113], v130, s[14:15] nt
	global_load_dwordx4 v[106:109], v130, s[14:15] offset:1024 nt
	global_load_dwordx4 v[102:105], v130, s[14:15] offset:2048 nt
	global_load_dwordx4 v[126:129], v130, s[16:17] nt
	global_load_dwordx4 v[122:125], v130, s[16:17] offset:1024 nt
	global_load_dwordx4 v[98:101], v130, s[14:15] offset:3072 nt
	global_load_dwordx4 v[118:121], v130, s[16:17] offset:2048 nt
	global_load_dwordx4 v[114:117], v130, s[16:17] offset:3072 nt
	global_load_dwordx4 v[58:61], v62, s[4:5] offset:16
	s_nop 0
	global_load_dwordx4 v[62:65], v62, s[4:5]
	s_add_u32 s12, s94, s12
	s_addc_u32 s13, s95, s13
	s_add_i32 s16, s8, s10
	s_ashr_i32 s11, s10, 31
	s_ashr_i32 s17, s16, 31
	s_lshl_b64 s[14:15], s[10:11], 12
	s_lshl_b64 s[16:17], s[16:17], 12
	s_add_u32 s16, s94, s16
	v_mov_b32_e32 v131, 0
	s_mov_b32 s9, 0x2f1e0000
	s_mov_b32 s22, 0x2f1e1000
	v_mov_b32_e32 v1, 0x358637bd
	s_mov_b32 s23, 0x1b500000
	v_mov_b32_e32 v132, 0x3a000000
	s_addc_u32 s17, s95, s17
	s_waitcnt vmcnt(9)
	v_mov_b64_e32 v[66:67], v[110:111]
	s_waitcnt vmcnt(8)
	v_mov_b64_e32 v[70:71], v[106:107]
	s_waitcnt vmcnt(7)
	v_mov_b64_e32 v[78:79], v[102:103]
	s_waitcnt vmcnt(6)
	v_mov_b64_e32 v[74:75], v[126:127]
	s_waitcnt vmcnt(5)
	v_mov_b64_e32 v[82:83], v[122:123]
	s_waitcnt vmcnt(4)
	v_mov_b64_e32 v[94:95], v[98:99]
	s_waitcnt vmcnt(3)
	v_mov_b64_e32 v[86:87], v[118:119]
	s_waitcnt vmcnt(2)
	v_mov_b64_e32 v[90:91], v[114:115]
	v_mov_b64_e32 v[68:69], v[112:113]
	v_mov_b64_e32 v[72:73], v[108:109]
	v_mov_b64_e32 v[80:81], v[104:105]
	v_mov_b64_e32 v[76:77], v[128:129]
	v_mov_b64_e32 v[84:85], v[124:125]
	v_mov_b64_e32 v[88:89], v[120:121]
	v_mov_b64_e32 v[92:93], v[116:117]
	v_mov_b64_e32 v[96:97], v[100:101]
	s_branch .LBB0_2914

.LBB0_3285:
	s_cmp_lt_i32 s42, 38
	s_cselect_b64 s[0:1], -1, 0
	s_cmp_gt_i32 s43, 37
	s_cselect_b64 s[4:5], -1, 0
	s_and_b64 s[0:1], s[0:1], s[4:5]
	s_andn2_b64 vcc, exec, s[0:1]
	s_cbranch_vccnz .LBB0_3365
	v_readlane_b32 s4, v254, 2
	v_readlane_b32 s14, v254, 12
	v_readlane_b32 s15, v254, 13
	v_readlane_b32 s18, v254, 16
	v_readlane_b32 s19, v254, 17
	v_readlane_b32 s6, v254, 4
	s_mov_b64 s[14:15], s[18:19]
	v_readlane_b32 s7, v254, 5
	s_add_u32 s6, s14, 0x2a000
	v_readlane_b32 s8, v254, 6
	s_addc_u32 s7, s15, 0
	v_readlane_b32 s9, v254, 7
	s_add_u32 s8, s14, 0x2c000
	v_readlane_b32 s10, v254, 8
	s_addc_u32 s9, s15, 0
	s_ashr_i32 s1, s90, 5
	s_abs_i32 s0, s1
	v_cvt_f32_u32_e32 v169, s0
	s_sub_i32 s10, 0, s0
	s_abs_i32 s4, s62
	s_xor_b32 s5, s62, s1
	v_rcp_iflag_f32_e32 v169, v169
	s_ashr_i32 s5, s5, 31
	v_mul_f32_e32 v169, 0x4f7ffffe, v169
	v_cvt_u32_f32_e32 v169, v169
	s_nop 0
	v_readfirstlane_b32 s11, v169
	s_mul_i32 s10, s10, s11
	s_mul_hi_u32 s10, s11, s10
	s_add_i32 s11, s11, s10
	s_mul_hi_u32 s10, s4, s11
	s_mul_i32 s11, s10, s0
	s_sub_i32 s4, s4, s11
	s_add_i32 s12, s10, 1
	s_sub_i32 s11, s4, s0
	s_cmp_ge_u32 s4, s0
	s_cselect_b32 s10, s12, s10
	s_cselect_b32 s4, s11, s4
	s_add_i32 s11, s10, 1
	s_cmp_ge_u32 s4, s0
	s_cselect_b32 s0, s11, s10
	s_xor_b32 s0, s0, s5
	s_sub_i32 s0, s0, s5
	s_mul_i32 s1, s0, s1
	s_sub_i32 s1, s62, s1
	s_cmp_lg_u32 s1, 0
	s_ashr_i32 s1, s0, 31
	s_lshl_b64 s[4:5], s[0:1], 13
	v_readlane_b32 s10, v254, 58
	v_readlane_b32 s11, v254, 59
	s_add_u32 s4, s10, s4
	s_addc_u32 s5, s11, s5
	v_mov_b32_e32 v179, 0
	v_lshlrev_b32_e32 v178, 4, v0
	v_lshl_add_u64 v[170:171], s[4:5], 0, v[178:179]
	v_add_co_u32_e32 v172, vcc, 0x40000, v170
	global_load_dwordx4 v[184:187], v178, s[4:5]
	s_nop 0
	v_addc_co_u32_e32 v173, vcc, 0, v171, vcc
	v_add_co_u32_e32 v174, vcc, 0x80000, v170
	s_add_i32 s4, s0, 0x2000
	s_nop 0
	v_addc_co_u32_e32 v175, vcc, 0, v171, vcc
	v_add_co_u32_e32 v170, vcc, 0xc0000, v170
	global_load_dwordx4 v[188:191], v[172:173], off
	global_load_dwordx4 v[192:195], v[174:175], off
	v_addc_co_u32_e32 v171, vcc, 0, v171, vcc
	global_load_dwordx4 v[196:199], v[170:171], off
	s_ashr_i32 s5, s4, 31
	s_lshl_b64 s[0:1], s[4:5], 12
	v_readlane_b32 s10, v254, 54
	v_readlane_b32 s11, v254, 55
	s_add_u32 s0, s10, s0
	s_addc_u32 s1, s11, s1
	v_lshlrev_b32_e32 v182, 3, v0
	global_load_dwordx4 v[174:177], v178, s[6:7]
	global_load_dwordx4 v[170:173], v178, s[8:9]
	global_load_dwordx2 v[180:181], v182, s[0:1]
	s_lshl_b32 s0, s62, 3
	s_add_i32 s10, s0, s96
	s_and_b32 s0, s0, 0xf8
	s_lshl_b32 s1, s62, 5
	v_readlane_b32 s11, v254, 9
	s_add_i32 s0, s0, s96
	s_and_b32 s1, s1, 0xfffffc00
	v_readlane_b32 s13, v254, 11
	s_add_i32 s11, s0, s1
	s_add_i32 s13, s11, 0x400
	s_cmpk_eq_i32 s90, 0x100
	v_readlane_b32 s5, v254, 3
	s_cselect_b64 s[0:1], -1, 0
	v_readlane_b32 s12, v254, 10
	s_and_b64 s[4:5], s[0:1], exec
	s_cselect_b32 s12, s11, s10
	s_cselect_b32 s11, s13, 0x2000
	s_cmp_ge_i32 s12, s11
	v_readlane_b32 s16, v254, 14
	v_readlane_b32 s17, v254, 15
	s_cbranch_scc1 .LBB0_3293
	s_lshl_b32 s4, s90, 3
	v_lshlrev_b32_e32 v1, 5, v166
	s_and_b64 s[0:1], s[0:1], exec
	v_or_b32_e32 v58, 0x800, v1
	v_or_b32_e32 v59, 0x1000, v1
	v_or_b32_e32 v66, 0x1800, v1
	s_cselect_b32 s14, 0x100, s4
	s_ashr_i32 s13, s12, 31
	global_load_dwordx4 v[2:5], v1, s[6:7] offset:16
	global_load_dwordx4 v[6:9], v1, s[6:7]
	global_load_dwordx4 v[10:13], v58, s[6:7] offset:16
	global_load_dwordx4 v[14:17], v58, s[6:7]
	global_load_dwordx4 v[18:21], v59, s[6:7] offset:16
	global_load_dwordx4 v[22:25], v59, s[6:7]
	global_load_dwordx4 v[26:29], v66, s[6:7] offset:16
	global_load_dwordx4 v[30:33], v66, s[6:7]
	global_load_dwordx4 v[34:37], v1, s[8:9] offset:16
	global_load_dwordx4 v[38:41], v1, s[8:9]
	global_load_dwordx4 v[42:45], v58, s[8:9] offset:16
	global_load_dwordx4 v[46:49], v58, s[8:9]
	global_load_dwordx4 v[50:53], v59, s[8:9] offset:16
	global_load_dwordx4 v[54:57], v59, s[8:9]
	s_lshl_b64 s[4:5], s[12:13], 11
	s_lshl_b64 s[16:17], s[12:13], 12
	v_readlane_b32 s0, v254, 54
	v_readlane_b32 s1, v254, 55
	s_add_u32 s0, s0, s16
	s_addc_u32 s1, s1, s17
	s_add_u32 s18, s80, s16
	v_lshlrev_b32_e32 v67, 4, v166
	s_addc_u32 s19, s81, s17
	global_load_dwordx4 v[110:113], v67, s[0:1] nt
	global_load_dwordx4 v[106:109], v67, s[0:1] offset:1024 nt
	global_load_dwordx4 v[102:105], v67, s[0:1] offset:2048 nt
	global_load_dwordx4 v[126:129], v67, s[18:19] nt
	global_load_dwordx4 v[122:125], v67, s[18:19] offset:1024 nt
	global_load_dwordx4 v[98:101], v67, s[0:1] offset:3072 nt
	global_load_dwordx4 v[118:121], v67, s[18:19] offset:2048 nt
	global_load_dwordx4 v[114:117], v67, s[18:19] offset:3072 nt
	global_load_dwordx4 v[58:61], v66, s[8:9] offset:16
	global_load_dwordx4 v[62:65], v66, s[8:9]
	v_lshl_or_b32 v130, v166, 3, s4
	v_mov_b32_e32 v131, s5
	s_lshl_b64 s[4:5], s[12:13], 2
	s_add_u32 s13, s4, 0x2ee80000
	s_addc_u32 s35, s5, 0
	s_add_i32 s4, s12, s14
	s_ashr_i32 s5, s4, 31
	s_lshl_b64 s[4:5], s[4:5], 12
	v_or_b32_e32 v132, s16, v67
	s_ashr_i32 s15, s14, 31
	v_or_b32_e32 v134, s4, v67
	v_cmp_eq_u32_e64 s[0:1], 0, v166
	s_mov_b32 s26, 0x2f1e0000
	s_mov_b32 s27, 0x2f1e1000
	v_mov_b32_e32 v1, 0
	v_mov_b32_e32 v136, 0x358637bd
	s_mov_b32 s28, 0x42fe0000
	s_mov_b32 s29, 0xc0c0400
	s_mov_b32 s30, 0xc040100
	s_mov_b32 s31, 0x4020100
	s_mov_b32 s34, 0x2de00000
	v_mov_b32_e32 v137, 0x3a000000
	v_mov_b32_e32 v138, 0x3c010204
	v_mov_b32_e32 v139, 0x42fe0000
	v_mov_b32_e32 v133, s17
	s_lshl_b64 s[16:17], s[14:15], 2
	s_lshl_b64 s[18:19], s[14:15], 11
	s_lshl_b64 s[20:21], s[14:15], 12
	v_mov_b32_e32 v135, s5
	s_waitcnt vmcnt(9)
	v_mov_b64_e32 v[66:67], v[110:111]
	s_waitcnt vmcnt(8)
	v_mov_b64_e32 v[70:71], v[106:107]
	s_waitcnt vmcnt(7)
	v_mov_b64_e32 v[78:79], v[102:103]
	s_waitcnt vmcnt(6)
	v_mov_b64_e32 v[74:75], v[126:127]
	s_waitcnt vmcnt(5)
	v_mov_b64_e32 v[82:83], v[122:123]
	s_waitcnt vmcnt(4)
	v_mov_b64_e32 v[94:95], v[98:99]
	s_waitcnt vmcnt(3)
	v_mov_b64_e32 v[86:87], v[118:119]
	s_waitcnt vmcnt(2)
	v_mov_b64_e32 v[90:91], v[114:115]
	v_mov_b64_e32 v[68:69], v[112:113]
	v_mov_b64_e32 v[72:73], v[108:109]
	v_mov_b64_e32 v[80:81], v[104:105]
	v_mov_b64_e32 v[76:77], v[128:129]
	v_mov_b64_e32 v[84:85], v[124:125]
	v_mov_b64_e32 v[88:89], v[120:121]
	v_mov_b64_e32 v[92:93], v[116:117]
	v_mov_b64_e32 v[96:97], v[100:101]
	s_branch .LBB0_3289

.LBB0_3557:
	s_cmp_lt_i32 s42, 41
	s_cselect_b64 s[0:1], -1, 0
	s_cmp_gt_i32 s43, 40
	s_cselect_b64 s[2:3], -1, 0
	s_and_b64 s[0:1], s[0:1], s[2:3]
	s_andn2_b64 vcc, exec, s[0:1]
	s_cbranch_vccnz .LBB0_3627
	v_readlane_b32 s0, v254, 2
	v_readlane_b32 s14, v254, 16
	v_readlane_b32 s1, v254, 3
	v_readlane_b32 s3, v254, 5
	v_readlane_b32 s15, v254, 17
	s_add_u32 s0, s14, 0x2e000
	v_readlane_b32 s2, v254, 4
	v_readlane_b32 s4, v254, 6
	s_addc_u32 s1, s15, 0
	s_lshl_b32 s3, s62, 3
	s_add_i32 s2, s3, s96
	s_and_b32 s3, s3, 0xf8
	s_lshl_b32 s4, s62, 5
	s_add_i32 s3, s3, s96
	s_and_b32 s4, s4, 0xfffffc00
	v_readlane_b32 s8, v254, 10
	s_add_i32 s3, s3, s4
	s_add_i32 s8, s3, 0x400
	v_readlane_b32 s6, v254, 8
	v_readlane_b32 s7, v254, 9
	s_cmpk_eq_i32 s90, 0x100
	v_readlane_b32 s5, v254, 7
	s_cselect_b64 s[6:7], -1, 0
	s_and_b64 s[4:5], s[6:7], exec
	s_cselect_b32 s4, s3, s2
	s_cselect_b32 s3, s8, 0x2000
	s_cmp_ge_i32 s4, s3
	v_readlane_b32 s9, v254, 11
	v_readlane_b32 s10, v254, 12
	v_readlane_b32 s11, v254, 13
	v_readlane_b32 s12, v254, 14
	v_readlane_b32 s13, v254, 15
	s_cbranch_scc1 .LBB0_3563
	s_lshl_b32 s5, s90, 3
	s_and_b64 s[6:7], s[6:7], exec
	s_cselect_b32 s6, 0x100, s5
	s_ashr_i32 s5, s4, 31
	s_lshl_b64 s[8:9], s[4:5], 12
	v_readlane_b32 s10, v254, 54
	v_lshlrev_b32_e32 v34, 5, v166
	v_readlane_b32 s11, v254, 55
	s_add_u32 s10, s10, s8
	v_or_b32_e32 v1, 0x800, v34
	s_addc_u32 s11, s11, s9
	global_load_dwordx4 v[2:5], v34, s[0:1] offset:16
	global_load_dwordx4 v[6:9], v34, s[0:1]
	global_load_dwordx4 v[10:13], v1, s[0:1] offset:16
	global_load_dwordx4 v[14:17], v1, s[0:1]
	v_or_b32_e32 v1, 0x1000, v34
	s_add_u32 s8, s80, s8
	v_lshlrev_b32_e32 v36, 4, v166
	global_load_dwordx4 v[18:21], v1, s[0:1] offset:16
	global_load_dwordx4 v[22:25], v1, s[0:1]
	v_or_b32_e32 v1, 0x1800, v34
	s_addc_u32 s9, s81, s9
	global_load_dwordx4 v[78:81], v36, s[10:11] nt
	global_load_dwordx4 v[74:77], v36, s[10:11] offset:1024 nt
	global_load_dwordx4 v[70:73], v36, s[10:11] offset:2048 nt
	global_load_dwordx4 v[94:97], v36, s[8:9] nt
	global_load_dwordx4 v[90:93], v36, s[8:9] offset:1024 nt
	global_load_dwordx4 v[66:69], v36, s[10:11] offset:3072 nt
	global_load_dwordx4 v[86:89], v36, s[8:9] offset:2048 nt
	global_load_dwordx4 v[82:85], v36, s[8:9] offset:3072 nt
	global_load_dwordx4 v[26:29], v1, s[0:1] offset:16
	global_load_dwordx4 v[30:33], v1, s[0:1]
	s_add_i32 s8, s4, s6
	s_ashr_i32 s9, s8, 31
	s_lshl_b64 s[8:9], s[8:9], 12
	s_add_u32 s8, s94, s8
	v_mov_b32_e32 v37, 0
	s_addc_u32 s9, s95, s9
	s_ashr_i32 s7, s6, 31
	v_mov_b32_e32 v35, v37
	s_lshl_b64 s[14:15], s[4:5], 13
	v_lshl_add_u64 v[36:37], s[8:9], 0, v[36:37]
	s_lshl_b64 s[8:9], s[6:7], 12
	s_add_u32 s14, s92, s14
	s_addc_u32 s15, s93, s15
	s_mov_b64 s[10:11], 0x29c00000
	s_mov_b64 s[12:13], 0x1000
	v_lshl_add_u64 v[34:35], s[14:15], 0, v[34:35]
	v_lshl_add_u64 v[98:99], v[36:37], 0, s[10:11]
	v_lshl_add_u64 v[100:101], v[34:35], 0, s[12:13]
	v_mov_b32_e32 v1, 0x358637bd
	v_mov_b32_e32 v102, 0x3a000000
	s_lshl_b64 s[10:11], s[6:7], 13
	s_waitcnt vmcnt(9)
	v_mov_b64_e32 v[34:35], v[78:79]
	s_waitcnt vmcnt(8)
	v_mov_b64_e32 v[38:39], v[74:75]
	s_waitcnt vmcnt(7)
	v_mov_b64_e32 v[50:51], v[70:71]
	s_waitcnt vmcnt(6)
	v_mov_b64_e32 v[42:43], v[94:95]
	s_waitcnt vmcnt(5)
	v_mov_b64_e32 v[46:47], v[90:91]
	s_waitcnt vmcnt(4)
	v_mov_b64_e32 v[58:59], v[66:67]
	s_waitcnt vmcnt(3)
	v_mov_b64_e32 v[54:55], v[86:87]
	s_waitcnt vmcnt(2)
	v_mov_b64_e32 v[62:63], v[82:83]
	v_mov_b64_e32 v[36:37], v[80:81]
	v_mov_b64_e32 v[40:41], v[76:77]
	v_mov_b64_e32 v[52:53], v[72:73]
	v_mov_b64_e32 v[44:45], v[96:97]
	v_mov_b64_e32 v[48:49], v[92:93]
	v_mov_b64_e32 v[56:57], v[88:89]
	v_mov_b64_e32 v[64:65], v[84:85]
	v_mov_b64_e32 v[60:61], v[68:69]
	s_branch .LBB0_3561
